# mixer LayerNorm statistics rewritten by hand (DPP reductions over 4 rows, double-buffered 16B loads) and a false vmcnt(0) removed from P1's unit-loop header
# baseline (speedup 1.0000x reference)
;     ...
;         const bool has_next = S.next(ui + 1, nxt);
;         const bool nrev = ZIGZAG && (((ui + 1) & 1) != 0);
;         const ptrdiff_t nk = has_next ? (nrev ? -kfwd : kfwd) : ck, noff = (has_next && nrev) ? kspan : 0;
;         const char* nA = has_next ? (const char*)g.A + (size_t)nxt.pm * tstep + noff : cA; const char* nB = has_next ? (const char*)g.Bt + (size_t)nxt.pn * tstep + noff : cB;
;     ...
; #pragma unroll
;         for (int a = 0; a < 2; ++a)
; #pragma unroll
;             for (int b = 0; b < 2; ++b)
; #pragma unroll
;                 for (int m = 0; m < 4; ++m)
; #pragma unroll
;                     for (int n = 0; n < 2; ++n) acc[a][b][m][n] = (f32x4){0.f, 0.f, 0.f, 0.f};
;         cur = nxt; cA = nA; cB = nB; ck = nk; ++ui;
.LBB0_243:
	s_ashr_i32 s21, s20, 31
	s_lshl_b64 s[24:25], s[20:21], 19
	s_add_u32 s24, s34, s24
	s_addc_u32 s25, s35, s25
	s_and_b64 s[26:27], s[0:1], exec
	s_cselect_b32 s21, s25, s41
	s_cselect_b32 s37, s24, s40
	s_ashr_i32 s23, s22, 31
	s_lshl_b64 s[26:27], s[22:23], 19
	s_add_u32 s26, s28, s26
	s_addc_u32 s27, s29, s27
	s_and_b64 s[48:49], s[0:1], exec
	s_cselect_b32 s23, s27, s45
	s_cselect_b32 s67, s26, s44
	s_add_u32 s40, s40, 0x40080
	s_addc_u32 s41, s41, 0
	s_add_u32 s68, s44, 0x100
	v_mov_b32_e32 v0, 0
	s_addc_u32 s69, s45, 0
	s_mov_b32 s70, -2
	v_mov_b32_e32 v1, v0
	v_mov_b32_e32 v2, v0
	v_mov_b32_e32 v3, v0
	v_mov_b32_e32 v4, v0
	v_mov_b32_e32 v5, v0
	v_mov_b32_e32 v6, v0
	v_mov_b32_e32 v7, v0
	v_mov_b32_e32 v16, v0
	v_mov_b32_e32 v17, v0
	v_mov_b32_e32 v18, v0
	v_mov_b32_e32 v19, v0
	v_mov_b32_e32 v20, v0
	v_mov_b32_e32 v21, v0
	v_mov_b32_e32 v22, v0
	v_mov_b32_e32 v23, v0
	v_mov_b32_e32 v32, v0
	v_mov_b32_e32 v33, v0
	v_mov_b32_e32 v34, v0
	v_mov_b32_e32 v35, v0
	v_mov_b32_e32 v36, v0
	v_mov_b32_e32 v37, v0
	v_mov_b32_e32 v38, v0
	v_mov_b32_e32 v39, v0
	v_mov_b32_e32 v48, v0
	v_mov_b32_e32 v49, v0
	v_mov_b32_e32 v50, v0
	v_mov_b32_e32 v51, v0
	v_mov_b32_e32 v52, v0
	v_mov_b32_e32 v53, v0
	v_mov_b32_e32 v54, v0
	v_mov_b32_e32 v55, v0
	v_mov_b32_e32 v8, v0
	v_mov_b32_e32 v9, v0
	v_mov_b32_e32 v10, v0
	v_mov_b32_e32 v11, v0
	v_mov_b32_e32 v12, v0
	v_mov_b32_e32 v13, v0
	v_mov_b32_e32 v14, v0
	v_mov_b32_e32 v15, v0
	v_mov_b32_e32 v24, v0
	v_mov_b32_e32 v25, v0
	v_mov_b32_e32 v26, v0
	v_mov_b32_e32 v27, v0
	v_mov_b32_e32 v28, v0
	v_mov_b32_e32 v29, v0
	v_mov_b32_e32 v30, v0
	v_mov_b32_e32 v31, v0
	v_mov_b32_e32 v40, v0
	v_mov_b32_e32 v41, v0
	v_mov_b32_e32 v42, v0
	v_mov_b32_e32 v43, v0
	v_mov_b32_e32 v44, v0
	v_mov_b32_e32 v45, v0
	v_mov_b32_e32 v46, v0
	v_mov_b32_e32 v47, v0
	v_mov_b32_e32 v56, v0
	v_mov_b32_e32 v57, v0
	v_mov_b32_e32 v58, v0
	v_mov_b32_e32 v59, v0
	v_mov_b32_e32 v60, v0
	v_mov_b32_e32 v61, v0
	v_mov_b32_e32 v62, v0
	v_mov_b32_e32 v63, v0
	v_mov_b32_e32 v64, v0
	v_mov_b32_e32 v65, v0
	v_mov_b32_e32 v66, v0
	v_mov_b32_e32 v67, v0
	v_mov_b32_e32 v68, v0
	v_mov_b32_e32 v69, v0
	v_mov_b32_e32 v70, v0
	v_mov_b32_e32 v71, v0
	v_mov_b32_e32 v80, v0
	v_mov_b32_e32 v81, v0
	v_mov_b32_e32 v82, v0
	v_mov_b32_e32 v83, v0
	v_mov_b32_e32 v84, v0
	v_mov_b32_e32 v85, v0
	v_mov_b32_e32 v86, v0
	v_mov_b32_e32 v87, v0
	v_mov_b32_e32 v96, v0
	v_mov_b32_e32 v97, v0
	v_mov_b32_e32 v98, v0
	v_mov_b32_e32 v99, v0
	v_mov_b32_e32 v100, v0
	v_mov_b32_e32 v101, v0
	v_mov_b32_e32 v102, v0
	v_mov_b32_e32 v103, v0
	v_mov_b32_e32 v112, v0
	v_mov_b32_e32 v113, v0
	v_mov_b32_e32 v114, v0
	v_mov_b32_e32 v115, v0
	v_mov_b32_e32 v116, v0
	v_mov_b32_e32 v117, v0
	v_mov_b32_e32 v118, v0
	v_mov_b32_e32 v119, v0
	v_mov_b32_e32 v72, v0
	v_mov_b32_e32 v73, v0
	v_mov_b32_e32 v74, v0
	v_mov_b32_e32 v75, v0
	v_mov_b32_e32 v76, v0
	v_mov_b32_e32 v77, v0
	v_mov_b32_e32 v78, v0
	v_mov_b32_e32 v79, v0
	v_mov_b32_e32 v88, v0
	v_mov_b32_e32 v89, v0
	v_mov_b32_e32 v90, v0
	v_mov_b32_e32 v91, v0
	v_mov_b32_e32 v92, v0
	v_mov_b32_e32 v93, v0
	v_mov_b32_e32 v94, v0
	v_mov_b32_e32 v95, v0
	v_mov_b32_e32 v104, v0
	v_mov_b32_e32 v105, v0
	v_mov_b32_e32 v106, v0
	v_mov_b32_e32 v107, v0
	v_mov_b32_e32 v108, v0
	v_mov_b32_e32 v109, v0
	v_mov_b32_e32 v110, v0
	v_mov_b32_e32 v111, v0
	v_mov_b32_e32 v120, v0
	v_mov_b32_e32 v121, v0
	v_mov_b32_e32 v122, v0
	v_mov_b32_e32 v123, v0
	v_mov_b32_e32 v124, v0
	v_mov_b32_e32 v125, v0
	v_mov_b32_e32 v126, v0
	v_mov_b32_e32 v127, v0

; __device__ __forceinline__ void unpack8(const v4u w, float (&x)[8]) { x[0] = bf_lo(w.x); x[1] = bf_hi(w.x); x[2] = bf_lo(w.y); x[3] = bf_hi(w.y); x[4] = bf_lo(w.z); x[5] = bf_hi(w.z); x[6] = bf_lo(w.w); x[7] = bf_hi(w.w); }
; __device__ __forceinline__ void mixer_phase(LAS unsigned char* lds, bf16* U  , const bf16* V, const bf16* C, bf16* Bout,
;                                             const bf16* wsb, const float* sgu_b, const float* sgu_g, const bf16* pwT, const float* pool_scale, int G, int bid) {
;     ...
;         for (int ib = 0; ib < 16; ib += 4) {
;             v4u raw[4][2];
; #pragma unroll
;             for (int i = 0; i < 4; ++i) { const v4u* vr = (const v4u*)(V + (size_t)(r0 + wid * 16 + ib + i) * D); raw[i][0] = vr[lane]; raw[i][1] = vr[lane + 64]; }
; #pragma unroll
;             for (int i = 0; i < 4; ++i) {
;                 float x[16]; { float a[8], b[8]; unpack8(raw[i][0], a); unpack8(raw[i][1], b);
; #pragma unroll
;                     for (int j = 0; j < 8; ++j) { x[j] = a[j]; x[8 + j] = b[j]; } }
;                 float sm = 0.f;
; #pragma unroll
;                 for (int j = 0; j < 16; ++j) sm += x[j];
;                 const float mean = wave_sum(sm) * (1.f / D);
.LBB0_678:
	s_ashr_i32 s39, s38, 31
	s_lshl_b64 s[12:13], s[38:39], 11
	s_add_u32 s56, s28, s12
	s_addc_u32 s57, s29, s13
	s_ashr_i32 s41, s40, 31
	s_lshl_b64 s[12:13], s[40:41], 11
	s_add_u32 s58, s28, s12
	s_addc_u32 s59, s29, s13
	s_ashr_i32 s45, s44, 31
	s_lshl_b64 s[12:13], s[44:45], 11
	s_add_u32 s60, s28, s12
	s_addc_u32 s61, s29, s13
	s_ashr_i32 s37, s36, 31
	s_lshl_b64 s[12:13], s[36:37], 11
	s_add_u32 s62, s28, s12
	s_addc_u32 s63, s29, s13
	s_mov_b32 s24, -4
	s_mov_b32 s37, s3
	s_add_u32 s12, s28, 0xd000000
	s_addc_u32 s13, s29, 0
	v_lshrrev_b32_e32 v80, 1, v134
	v_add_u32_e32 v80, s37, v80
	s_add_u32 s24, s36, 0
	s_lshl_b32 s24, s24, 11
	v_add_u32_e32 v40, s24, v134
	v_add_u32_e32 v43, 0x1000, v40
	global_load_dwordx4 v[0:3], v40, s[12:13]
	global_load_dwordx4 v[4:7], v40, s[12:13] offset:1024
	global_load_dwordx4 v[8:11], v40, s[12:13] offset:2048
	global_load_dwordx4 v[12:15], v40, s[12:13] offset:3072
	global_load_dwordx4 v[16:19], v43, s[12:13]
	global_load_dwordx4 v[20:23], v43, s[12:13] offset:1024
	global_load_dwordx4 v[24:27], v43, s[12:13] offset:2048
	global_load_dwordx4 v[28:31], v43, s[12:13] offset:3072
	s_add_u32 s24, s36, 4
	s_lshl_b32 s24, s24, 11
	v_add_u32_e32 v76, s24, v134
	v_add_u32_e32 v77, 0x1000, v76
	global_load_dwordx4 v[44:47], v76, s[12:13]
	global_load_dwordx4 v[48:51], v76, s[12:13] offset:1024
	global_load_dwordx4 v[52:55], v76, s[12:13] offset:2048
	global_load_dwordx4 v[56:59], v76, s[12:13] offset:3072
	global_load_dwordx4 v[60:63], v77, s[12:13]
	global_load_dwordx4 v[64:67], v77, s[12:13] offset:1024
	global_load_dwordx4 v[68:71], v77, s[12:13] offset:2048
	global_load_dwordx4 v[72:75], v77, s[12:13] offset:3072
	s_waitcnt vmcnt(8)
	v_lshlrev_b32_e32 v41, 16, v0
	v_and_b32_e32 v42, 0xffff0000, v0
	v_add_f32_e32 v32, v41, v42
	v_lshlrev_b32_e32 v41, 16, v1
	v_and_b32_e32 v42, 0xffff0000, v1
	v_add_f32_e32 v32, v32, v41
	v_add_f32_e32 v32, v32, v42
	v_lshlrev_b32_e32 v41, 16, v2
	v_and_b32_e32 v42, 0xffff0000, v2
	v_add_f32_e32 v32, v32, v41
	v_add_f32_e32 v32, v32, v42
	v_lshlrev_b32_e32 v41, 16, v3
	v_and_b32_e32 v42, 0xffff0000, v3
	v_add_f32_e32 v32, v32, v41
	v_add_f32_e32 v32, v32, v42
	v_lshlrev_b32_e32 v41, 16, v4
	v_and_b32_e32 v42, 0xffff0000, v4
	v_add_f32_e32 v32, v32, v41
	v_add_f32_e32 v32, v32, v42
	v_lshlrev_b32_e32 v41, 16, v5
	v_and_b32_e32 v42, 0xffff0000, v5
	v_add_f32_e32 v32, v32, v41
	v_add_f32_e32 v32, v32, v42
	v_lshlrev_b32_e32 v41, 16, v6
	v_and_b32_e32 v42, 0xffff0000, v6
	v_add_f32_e32 v32, v32, v41
	v_add_f32_e32 v32, v32, v42
	v_lshlrev_b32_e32 v41, 16, v7
	v_and_b32_e32 v42, 0xffff0000, v7
	v_add_f32_e32 v32, v32, v41
	v_add_f32_e32 v32, v32, v42
	v_lshlrev_b32_e32 v41, 16, v8
	v_and_b32_e32 v42, 0xffff0000, v8
	v_add_f32_e32 v33, v41, v42
	v_lshlrev_b32_e32 v41, 16, v9
	v_and_b32_e32 v42, 0xffff0000, v9
	v_add_f32_e32 v33, v33, v41
	v_add_f32_e32 v33, v33, v42
	v_lshlrev_b32_e32 v41, 16, v10
	v_and_b32_e32 v42, 0xffff0000, v10
	v_add_f32_e32 v33, v33, v41
	v_add_f32_e32 v33, v33, v42
	v_lshlrev_b32_e32 v41, 16, v11
	v_and_b32_e32 v42, 0xffff0000, v11
	v_add_f32_e32 v33, v33, v41
	v_add_f32_e32 v33, v33, v42
	v_lshlrev_b32_e32 v41, 16, v12
	v_and_b32_e32 v42, 0xffff0000, v12
	v_add_f32_e32 v33, v33, v41
	v_add_f32_e32 v33, v33, v42
	v_lshlrev_b32_e32 v41, 16, v13
	v_and_b32_e32 v42, 0xffff0000, v13
	v_add_f32_e32 v33, v33, v41
	v_add_f32_e32 v33, v33, v42
	v_lshlrev_b32_e32 v41, 16, v14
	v_and_b32_e32 v42, 0xffff0000, v14
	v_add_f32_e32 v33, v33, v41
	v_add_f32_e32 v33, v33, v42
	v_lshlrev_b32_e32 v41, 16, v15
	v_and_b32_e32 v42, 0xffff0000, v15
	v_add_f32_e32 v33, v33, v41
	v_add_f32_e32 v33, v33, v42
	v_lshlrev_b32_e32 v41, 16, v16
	v_and_b32_e32 v42, 0xffff0000, v16
	v_add_f32_e32 v34, v41, v42
	v_lshlrev_b32_e32 v41, 16, v17
	v_and_b32_e32 v42, 0xffff0000, v17
	v_add_f32_e32 v34, v34, v41
	v_add_f32_e32 v34, v34, v42
	v_lshlrev_b32_e32 v41, 16, v18
	v_and_b32_e32 v42, 0xffff0000, v18
	v_add_f32_e32 v34, v34, v41
	v_add_f32_e32 v34, v34, v42
	v_lshlrev_b32_e32 v41, 16, v19
	v_and_b32_e32 v42, 0xffff0000, v19
	v_add_f32_e32 v34, v34, v41
	v_add_f32_e32 v34, v34, v42
	v_lshlrev_b32_e32 v41, 16, v20
	v_and_b32_e32 v42, 0xffff0000, v20
	v_add_f32_e32 v34, v34, v41
	v_add_f32_e32 v34, v34, v42
	v_lshlrev_b32_e32 v41, 16, v21
	v_and_b32_e32 v42, 0xffff0000, v21
	v_add_f32_e32 v34, v34, v41
	v_add_f32_e32 v34, v34, v42
	v_lshlrev_b32_e32 v41, 16, v22
	v_and_b32_e32 v42, 0xffff0000, v22
	v_add_f32_e32 v34, v34, v41
	v_add_f32_e32 v34, v34, v42
	v_lshlrev_b32_e32 v41, 16, v23
	v_and_b32_e32 v42, 0xffff0000, v23
	v_add_f32_e32 v34, v34, v41
	v_add_f32_e32 v34, v34, v42
	v_lshlrev_b32_e32 v41, 16, v24
	v_and_b32_e32 v42, 0xffff0000, v24
	v_add_f32_e32 v35, v41, v42
	v_lshlrev_b32_e32 v41, 16, v25
	v_and_b32_e32 v42, 0xffff0000, v25
	v_add_f32_e32 v35, v35, v41
	v_add_f32_e32 v35, v35, v42
	v_lshlrev_b32_e32 v41, 16, v26
	v_and_b32_e32 v42, 0xffff0000, v26
	v_add_f32_e32 v35, v35, v41
	v_add_f32_e32 v35, v35, v42
	v_lshlrev_b32_e32 v41, 16, v27
	v_and_b32_e32 v42, 0xffff0000, v27
	v_add_f32_e32 v35, v35, v41
	v_add_f32_e32 v35, v35, v42
	v_lshlrev_b32_e32 v41, 16, v28
	v_and_b32_e32 v42, 0xffff0000, v28
	v_add_f32_e32 v35, v35, v41
	v_add_f32_e32 v35, v35, v42
	v_lshlrev_b32_e32 v41, 16, v29
	v_and_b32_e32 v42, 0xffff0000, v29
	v_add_f32_e32 v35, v35, v41
	v_add_f32_e32 v35, v35, v42
	v_lshlrev_b32_e32 v41, 16, v30
	v_and_b32_e32 v42, 0xffff0000, v30
	v_add_f32_e32 v35, v35, v41
	v_add_f32_e32 v35, v35, v42
	v_lshlrev_b32_e32 v41, 16, v31
	v_and_b32_e32 v42, 0xffff0000, v31
	v_add_f32_e32 v35, v35, v41
	v_add_f32_e32 v35, v35, v42
	s_nop 1
; __device__ __forceinline__ void unpack8(const v4u w, float (&x)[8]) { x[0] = bf_lo(w.x); x[1] = bf_hi(w.x); x[2] = bf_lo(w.y); x[3] = bf_hi(w.y); x[4] = bf_lo(w.z); x[5] = bf_hi(w.z); x[6] = bf_lo(w.w); x[7] = bf_hi(w.w); }
; __device__ __forceinline__ void mixer_phase(LAS unsigned char* lds, bf16* U  , const bf16* V, const bf16* C, bf16* Bout,
;                                             const bf16* wsb, const float* sgu_b, const float* sgu_g, const bf16* pwT, const float* pool_scale, int G, int bid) {
;     ...
;             for (int i = 0; i < 4; ++i) {
;                 float x[16]; { float a[8], b[8]; unpack8(raw[i][0], a); unpack8(raw[i][1], b);
; #pragma unroll
;                     for (int j = 0; j < 8; ++j) { x[j] = a[j]; x[8 + j] = b[j]; } }
;                 float sm = 0.f;
; #pragma unroll
;                 for (int j = 0; j < 16; ++j) sm += x[j];
;                 const float mean = wave_sum(sm) * (1.f / D);
;                 float sq = 0.f;
; #pragma unroll
;                 for (int j = 0; j < 16; ++j) { const float d = x[j] - mean; sq += d * d; }
;                 const float rstd = 1.0f / sqrtf(wave_sum(sq) * (1.f / D) + EPS);
	v_add_f32_dpp v32, v32, v32 quad_perm:[1,0,3,2] row_mask:0xf bank_mask:0xf
	v_add_f32_dpp v33, v33, v33 quad_perm:[1,0,3,2] row_mask:0xf bank_mask:0xf
	v_add_f32_dpp v34, v34, v34 quad_perm:[1,0,3,2] row_mask:0xf bank_mask:0xf
	v_add_f32_dpp v35, v35, v35 quad_perm:[1,0,3,2] row_mask:0xf bank_mask:0xf
	v_add_f32_dpp v32, v32, v32 quad_perm:[2,3,0,1] row_mask:0xf bank_mask:0xf
	v_add_f32_dpp v33, v33, v33 quad_perm:[2,3,0,1] row_mask:0xf bank_mask:0xf
	v_add_f32_dpp v34, v34, v34 quad_perm:[2,3,0,1] row_mask:0xf bank_mask:0xf
	v_add_f32_dpp v35, v35, v35 quad_perm:[2,3,0,1] row_mask:0xf bank_mask:0xf
	v_add_f32_dpp v32, v32, v32 row_half_mirror row_mask:0xf bank_mask:0xf
	v_add_f32_dpp v33, v33, v33 row_half_mirror row_mask:0xf bank_mask:0xf
	v_add_f32_dpp v34, v34, v34 row_half_mirror row_mask:0xf bank_mask:0xf
	v_add_f32_dpp v35, v35, v35 row_half_mirror row_mask:0xf bank_mask:0xf
	v_add_f32_dpp v32, v32, v32 row_mirror row_mask:0xf bank_mask:0xf
	v_add_f32_dpp v33, v33, v33 row_mirror row_mask:0xf bank_mask:0xf
	v_add_f32_dpp v34, v34, v34 row_mirror row_mask:0xf bank_mask:0xf
	v_add_f32_dpp v35, v35, v35 row_mirror row_mask:0xf bank_mask:0xf
	v_add_f32_dpp v32, v32, v32 row_bcast:15 row_mask:0xa bank_mask:0xf
	v_add_f32_dpp v33, v33, v33 row_bcast:15 row_mask:0xa bank_mask:0xf
	v_add_f32_dpp v34, v34, v34 row_bcast:15 row_mask:0xa bank_mask:0xf
	v_add_f32_dpp v35, v35, v35 row_bcast:15 row_mask:0xa bank_mask:0xf
	v_add_f32_dpp v32, v32, v32 row_bcast:31 row_mask:0xc bank_mask:0xf
	v_add_f32_dpp v33, v33, v33 row_bcast:31 row_mask:0xc bank_mask:0xf
	v_add_f32_dpp v34, v34, v34 row_bcast:31 row_mask:0xc bank_mask:0xf
	v_add_f32_dpp v35, v35, v35 row_bcast:31 row_mask:0xc bank_mask:0xf
	v_mul_f32_e32 v32, 0x3a800000, v32
	v_mul_f32_e32 v33, 0x3a800000, v33
	v_mul_f32_e32 v34, 0x3a800000, v34
	v_mul_f32_e32 v35, 0x3a800000, v35
	s_nop 0
	v_readlane_b32 s56, v32, 63
	v_readlane_b32 s57, v33, 63
	v_readlane_b32 s58, v34, 63
	v_readlane_b32 s59, v35, 63
	s_nop 1
	v_mov_b32_e32 v36, 0
	v_lshlrev_b32_e32 v41, 16, v0
	v_and_b32_e32 v42, 0xffff0000, v0
	v_subrev_f32_e32 v41, s56, v41
	v_subrev_f32_e32 v42, s56, v42
	v_fmac_f32_e32 v36, v41, v41
	v_fmac_f32_e32 v36, v42, v42
	v_lshlrev_b32_e32 v41, 16, v1
	v_and_b32_e32 v42, 0xffff0000, v1
	v_subrev_f32_e32 v41, s56, v41
	v_subrev_f32_e32 v42, s56, v42
	v_fmac_f32_e32 v36, v41, v41
	v_fmac_f32_e32 v36, v42, v42
	v_lshlrev_b32_e32 v41, 16, v2
	v_and_b32_e32 v42, 0xffff0000, v2
	v_subrev_f32_e32 v41, s56, v41
	v_subrev_f32_e32 v42, s56, v42
	v_fmac_f32_e32 v36, v41, v41
	v_fmac_f32_e32 v36, v42, v42
	v_lshlrev_b32_e32 v41, 16, v3
	v_and_b32_e32 v42, 0xffff0000, v3
	v_subrev_f32_e32 v41, s56, v41
	v_subrev_f32_e32 v42, s56, v42
	v_fmac_f32_e32 v36, v41, v41
	v_fmac_f32_e32 v36, v42, v42
	v_lshlrev_b32_e32 v41, 16, v4
	v_and_b32_e32 v42, 0xffff0000, v4
	v_subrev_f32_e32 v41, s56, v41
	v_subrev_f32_e32 v42, s56, v42
	v_fmac_f32_e32 v36, v41, v41
	v_fmac_f32_e32 v36, v42, v42
	v_lshlrev_b32_e32 v41, 16, v5
	v_and_b32_e32 v42, 0xffff0000, v5
	v_subrev_f32_e32 v41, s56, v41
	v_subrev_f32_e32 v42, s56, v42
	v_fmac_f32_e32 v36, v41, v41
	v_fmac_f32_e32 v36, v42, v42
	v_lshlrev_b32_e32 v41, 16, v6
	v_and_b32_e32 v42, 0xffff0000, v6
	v_subrev_f32_e32 v41, s56, v41
	v_subrev_f32_e32 v42, s56, v42
	v_fmac_f32_e32 v36, v41, v41
	v_fmac_f32_e32 v36, v42, v42
	v_lshlrev_b32_e32 v41, 16, v7
	v_and_b32_e32 v42, 0xffff0000, v7
	v_subrev_f32_e32 v41, s56, v41
	v_subrev_f32_e32 v42, s56, v42
	v_fmac_f32_e32 v36, v41, v41
	v_fmac_f32_e32 v36, v42, v42
	v_mov_b32_e32 v37, 0
	v_lshlrev_b32_e32 v41, 16, v8
	v_and_b32_e32 v42, 0xffff0000, v8
	v_subrev_f32_e32 v41, s57, v41
	v_subrev_f32_e32 v42, s57, v42
	v_fmac_f32_e32 v37, v41, v41
	v_fmac_f32_e32 v37, v42, v42
	v_lshlrev_b32_e32 v41, 16, v9
	v_and_b32_e32 v42, 0xffff0000, v9
	v_subrev_f32_e32 v41, s57, v41
	v_subrev_f32_e32 v42, s57, v42
	v_fmac_f32_e32 v37, v41, v41
	v_fmac_f32_e32 v37, v42, v42
	v_lshlrev_b32_e32 v41, 16, v10
	v_and_b32_e32 v42, 0xffff0000, v10
	v_subrev_f32_e32 v41, s57, v41
	v_subrev_f32_e32 v42, s57, v42
	v_fmac_f32_e32 v37, v41, v41
	v_fmac_f32_e32 v37, v42, v42
	v_lshlrev_b32_e32 v41, 16, v11
	v_and_b32_e32 v42, 0xffff0000, v11
	v_subrev_f32_e32 v41, s57, v41
	v_subrev_f32_e32 v42, s57, v42
	v_fmac_f32_e32 v37, v41, v41
	v_fmac_f32_e32 v37, v42, v42
	v_lshlrev_b32_e32 v41, 16, v12
	v_and_b32_e32 v42, 0xffff0000, v12
	v_subrev_f32_e32 v41, s57, v41
	v_subrev_f32_e32 v42, s57, v42
	v_fmac_f32_e32 v37, v41, v41
	v_fmac_f32_e32 v37, v42, v42
	v_lshlrev_b32_e32 v41, 16, v13
	v_and_b32_e32 v42, 0xffff0000, v13
	v_subrev_f32_e32 v41, s57, v41
	v_subrev_f32_e32 v42, s57, v42
	v_fmac_f32_e32 v37, v41, v41
	v_fmac_f32_e32 v37, v42, v42
	v_lshlrev_b32_e32 v41, 16, v14
	v_and_b32_e32 v42, 0xffff0000, v14
	v_subrev_f32_e32 v41, s57, v41
	v_subrev_f32_e32 v42, s57, v42
	v_fmac_f32_e32 v37, v41, v41
	v_fmac_f32_e32 v37, v42, v42
	v_lshlrev_b32_e32 v41, 16, v15
	v_and_b32_e32 v42, 0xffff0000, v15
	v_subrev_f32_e32 v41, s57, v41
	v_subrev_f32_e32 v42, s57, v42
	v_fmac_f32_e32 v37, v41, v41
	v_fmac_f32_e32 v37, v42, v42
	v_mov_b32_e32 v38, 0
	v_lshlrev_b32_e32 v41, 16, v16
	v_and_b32_e32 v42, 0xffff0000, v16
	v_subrev_f32_e32 v41, s58, v41
	v_subrev_f32_e32 v42, s58, v42
	v_fmac_f32_e32 v38, v41, v41
	v_fmac_f32_e32 v38, v42, v42
	v_lshlrev_b32_e32 v41, 16, v17
	v_and_b32_e32 v42, 0xffff0000, v17
	v_subrev_f32_e32 v41, s58, v41
	v_subrev_f32_e32 v42, s58, v42
	v_fmac_f32_e32 v38, v41, v41
	v_fmac_f32_e32 v38, v42, v42
	v_lshlrev_b32_e32 v41, 16, v18
	v_and_b32_e32 v42, 0xffff0000, v18
	v_subrev_f32_e32 v41, s58, v41
	v_subrev_f32_e32 v42, s58, v42
; __device__ __forceinline__ void mixer_phase(LAS unsigned char* lds, bf16* U  , const bf16* V, const bf16* C, bf16* Bout,
;                                             const bf16* wsb, const float* sgu_b, const float* sgu_g, const bf16* pwT, const float* pool_scale, int G, int bid) {
;     ...
;             for (int i = 0; i < 4; ++i) { const v4u* vr = (const v4u*)(V + (size_t)(r0 + wid * 16 + ib + i) * D); raw[i][0] = vr[lane]; raw[i][1] = vr[lane + 64]; }
;     ...
;                 float sm = 0.f;
; #pragma unroll
;                 for (int j = 0; j < 16; ++j) sm += x[j];
;                 const float mean = wave_sum(sm) * (1.f / D);
;                 float sq = 0.f;
; #pragma unroll
;                 for (int j = 0; j < 16; ++j) { const float d = x[j] - mean; sq += d * d; }
;                 const float rstd = 1.0f / sqrtf(wave_sum(sq) * (1.f / D) + EPS);
;                 if (lane == 0) { const int sr = wid * 16 + ib + i; stat[2 * sr] = mean; stat[2 * sr + 1] = rstd; }
	v_fmac_f32_e32 v38, v41, v41
	v_fmac_f32_e32 v38, v42, v42
	v_lshlrev_b32_e32 v41, 16, v19
	v_and_b32_e32 v42, 0xffff0000, v19
	v_subrev_f32_e32 v41, s58, v41
	v_subrev_f32_e32 v42, s58, v42
	v_fmac_f32_e32 v38, v41, v41
	v_fmac_f32_e32 v38, v42, v42
	v_lshlrev_b32_e32 v41, 16, v20
	v_and_b32_e32 v42, 0xffff0000, v20
	v_subrev_f32_e32 v41, s58, v41
	v_subrev_f32_e32 v42, s58, v42
	v_fmac_f32_e32 v38, v41, v41
	v_fmac_f32_e32 v38, v42, v42
	v_lshlrev_b32_e32 v41, 16, v21
	v_and_b32_e32 v42, 0xffff0000, v21
	v_subrev_f32_e32 v41, s58, v41
	v_subrev_f32_e32 v42, s58, v42
	v_fmac_f32_e32 v38, v41, v41
	v_fmac_f32_e32 v38, v42, v42
	v_lshlrev_b32_e32 v41, 16, v22
	v_and_b32_e32 v42, 0xffff0000, v22
	v_subrev_f32_e32 v41, s58, v41
	v_subrev_f32_e32 v42, s58, v42
	v_fmac_f32_e32 v38, v41, v41
	v_fmac_f32_e32 v38, v42, v42
	v_lshlrev_b32_e32 v41, 16, v23
	v_and_b32_e32 v42, 0xffff0000, v23
	v_subrev_f32_e32 v41, s58, v41
	v_subrev_f32_e32 v42, s58, v42
	v_fmac_f32_e32 v38, v41, v41
	v_fmac_f32_e32 v38, v42, v42
	v_mov_b32_e32 v39, 0
	v_lshlrev_b32_e32 v41, 16, v24
	v_and_b32_e32 v42, 0xffff0000, v24
	v_subrev_f32_e32 v41, s59, v41
	v_subrev_f32_e32 v42, s59, v42
	v_fmac_f32_e32 v39, v41, v41
	v_fmac_f32_e32 v39, v42, v42
	v_lshlrev_b32_e32 v41, 16, v25
	v_and_b32_e32 v42, 0xffff0000, v25
	v_subrev_f32_e32 v41, s59, v41
	v_subrev_f32_e32 v42, s59, v42
	v_fmac_f32_e32 v39, v41, v41
	v_fmac_f32_e32 v39, v42, v42
	v_lshlrev_b32_e32 v41, 16, v26
	v_and_b32_e32 v42, 0xffff0000, v26
	v_subrev_f32_e32 v41, s59, v41
	v_subrev_f32_e32 v42, s59, v42
	v_fmac_f32_e32 v39, v41, v41
	v_fmac_f32_e32 v39, v42, v42
	v_lshlrev_b32_e32 v41, 16, v27
	v_and_b32_e32 v42, 0xffff0000, v27
	v_subrev_f32_e32 v41, s59, v41
	v_subrev_f32_e32 v42, s59, v42
	v_fmac_f32_e32 v39, v41, v41
	v_fmac_f32_e32 v39, v42, v42
	v_lshlrev_b32_e32 v41, 16, v28
	v_and_b32_e32 v42, 0xffff0000, v28
	v_subrev_f32_e32 v41, s59, v41
	v_subrev_f32_e32 v42, s59, v42
	v_fmac_f32_e32 v39, v41, v41
	v_fmac_f32_e32 v39, v42, v42
	v_lshlrev_b32_e32 v41, 16, v29
	v_and_b32_e32 v42, 0xffff0000, v29
	v_subrev_f32_e32 v41, s59, v41
	v_subrev_f32_e32 v42, s59, v42
	v_fmac_f32_e32 v39, v41, v41
	v_fmac_f32_e32 v39, v42, v42
	v_lshlrev_b32_e32 v41, 16, v30
	v_and_b32_e32 v42, 0xffff0000, v30
	v_subrev_f32_e32 v41, s59, v41
	v_subrev_f32_e32 v42, s59, v42
	v_fmac_f32_e32 v39, v41, v41
	v_fmac_f32_e32 v39, v42, v42
	v_lshlrev_b32_e32 v41, 16, v31
	v_and_b32_e32 v42, 0xffff0000, v31
	v_subrev_f32_e32 v41, s59, v41
	v_subrev_f32_e32 v42, s59, v42
	v_fmac_f32_e32 v39, v41, v41
	v_fmac_f32_e32 v39, v42, v42
	s_nop 1
	v_add_f32_dpp v36, v36, v36 quad_perm:[1,0,3,2] row_mask:0xf bank_mask:0xf
	v_add_f32_dpp v37, v37, v37 quad_perm:[1,0,3,2] row_mask:0xf bank_mask:0xf
	v_add_f32_dpp v38, v38, v38 quad_perm:[1,0,3,2] row_mask:0xf bank_mask:0xf
	v_add_f32_dpp v39, v39, v39 quad_perm:[1,0,3,2] row_mask:0xf bank_mask:0xf
	v_add_f32_dpp v36, v36, v36 quad_perm:[2,3,0,1] row_mask:0xf bank_mask:0xf
	v_add_f32_dpp v37, v37, v37 quad_perm:[2,3,0,1] row_mask:0xf bank_mask:0xf
	v_add_f32_dpp v38, v38, v38 quad_perm:[2,3,0,1] row_mask:0xf bank_mask:0xf
	v_add_f32_dpp v39, v39, v39 quad_perm:[2,3,0,1] row_mask:0xf bank_mask:0xf
	v_add_f32_dpp v36, v36, v36 row_half_mirror row_mask:0xf bank_mask:0xf
	v_add_f32_dpp v37, v37, v37 row_half_mirror row_mask:0xf bank_mask:0xf
	v_add_f32_dpp v38, v38, v38 row_half_mirror row_mask:0xf bank_mask:0xf
	v_add_f32_dpp v39, v39, v39 row_half_mirror row_mask:0xf bank_mask:0xf
	v_add_f32_dpp v36, v36, v36 row_mirror row_mask:0xf bank_mask:0xf
	v_add_f32_dpp v37, v37, v37 row_mirror row_mask:0xf bank_mask:0xf
	v_add_f32_dpp v38, v38, v38 row_mirror row_mask:0xf bank_mask:0xf
	v_add_f32_dpp v39, v39, v39 row_mirror row_mask:0xf bank_mask:0xf
	v_add_f32_dpp v36, v36, v36 row_bcast:15 row_mask:0xa bank_mask:0xf
	v_add_f32_dpp v37, v37, v37 row_bcast:15 row_mask:0xa bank_mask:0xf
	v_add_f32_dpp v38, v38, v38 row_bcast:15 row_mask:0xa bank_mask:0xf
	v_add_f32_dpp v39, v39, v39 row_bcast:15 row_mask:0xa bank_mask:0xf
	v_add_f32_dpp v36, v36, v36 row_bcast:31 row_mask:0xc bank_mask:0xf
	v_add_f32_dpp v37, v37, v37 row_bcast:31 row_mask:0xc bank_mask:0xf
	v_add_f32_dpp v38, v38, v38 row_bcast:31 row_mask:0xc bank_mask:0xf
	v_add_f32_dpp v39, v39, v39 row_bcast:31 row_mask:0xc bank_mask:0xf
	v_mul_f32_e32 v36, 0x3a800000, v36
	v_mul_f32_e32 v37, 0x3a800000, v37
	v_mul_f32_e32 v38, 0x3a800000, v38
	v_mul_f32_e32 v39, 0x3a800000, v39
	v_add_f32_e32 v36, 0x358637bd, v36
	v_add_f32_e32 v37, 0x358637bd, v37
	v_add_f32_e32 v38, 0x358637bd, v38
	v_add_f32_e32 v39, 0x358637bd, v39
	v_rsq_f32_e32 v36, v36
	v_rsq_f32_e32 v37, v37
	v_rsq_f32_e32 v38, v38
	v_rsq_f32_e32 v39, v39
	s_nop 0
	v_readlane_b32 s62, v36, 63
	v_readlane_b32 s63, v37, 63
	v_readlane_b32 s64, v38, 63
	v_readlane_b32 s65, v39, 63
	s_nop 3
	v_writelane_b32 v78, s56, 0
	v_writelane_b32 v79, s62, 0
	v_writelane_b32 v78, s57, 1
	v_writelane_b32 v79, s63, 1
	v_writelane_b32 v78, s58, 2
	v_writelane_b32 v79, s64, 2
	v_writelane_b32 v78, s59, 3
	v_writelane_b32 v79, s65, 3
	s_mov_b64 exec, 15
	ds_write_b64 v80, v[78:79]
	s_mov_b64 exec, -1
	s_add_u32 s24, s36, 8
	s_lshl_b32 s24, s24, 11
	v_add_u32_e32 v40, s24, v134
	v_add_u32_e32 v43, 0x1000, v40
	global_load_dwordx4 v[0:3], v40, s[12:13]
	global_load_dwordx4 v[4:7], v40, s[12:13] offset:1024
	global_load_dwordx4 v[8:11], v40, s[12:13] offset:2048
	global_load_dwordx4 v[12:15], v40, s[12:13] offset:3072
	global_load_dwordx4 v[16:19], v43, s[12:13]
	global_load_dwordx4 v[20:23], v43, s[12:13] offset:1024
	global_load_dwordx4 v[24:27], v43, s[12:13] offset:2048
	global_load_dwordx4 v[28:31], v43, s[12:13] offset:3072
	s_waitcnt vmcnt(8)
; __device__ __forceinline__ void unpack8(const v4u w, float (&x)[8]) { x[0] = bf_lo(w.x); x[1] = bf_hi(w.x); x[2] = bf_lo(w.y); x[3] = bf_hi(w.y); x[4] = bf_lo(w.z); x[5] = bf_hi(w.z); x[6] = bf_lo(w.w); x[7] = bf_hi(w.w); }
; __device__ __forceinline__ void mixer_phase(LAS unsigned char* lds, bf16* U  , const bf16* V, const bf16* C, bf16* Bout,
;                                             const bf16* wsb, const float* sgu_b, const float* sgu_g, const bf16* pwT, const float* pool_scale, int G, int bid) {
;     ...
;                 float x[16]; { float a[8], b[8]; unpack8(raw[i][0], a); unpack8(raw[i][1], b);
; #pragma unroll
;                     for (int j = 0; j < 8; ++j) { x[j] = a[j]; x[8 + j] = b[j]; } }
;                 float sm = 0.f;
; #pragma unroll
;                 for (int j = 0; j < 16; ++j) sm += x[j];
;                 const float mean = wave_sum(sm) * (1.f / D);
	v_lshlrev_b32_e32 v41, 16, v44
	v_and_b32_e32 v42, 0xffff0000, v44
	v_add_f32_e32 v32, v41, v42
	v_lshlrev_b32_e32 v41, 16, v45
	v_and_b32_e32 v42, 0xffff0000, v45
	v_add_f32_e32 v32, v32, v41
	v_add_f32_e32 v32, v32, v42
	v_lshlrev_b32_e32 v41, 16, v46
	v_and_b32_e32 v42, 0xffff0000, v46
	v_add_f32_e32 v32, v32, v41
	v_add_f32_e32 v32, v32, v42
	v_lshlrev_b32_e32 v41, 16, v47
	v_and_b32_e32 v42, 0xffff0000, v47
	v_add_f32_e32 v32, v32, v41
	v_add_f32_e32 v32, v32, v42
	v_lshlrev_b32_e32 v41, 16, v48
	v_and_b32_e32 v42, 0xffff0000, v48
	v_add_f32_e32 v32, v32, v41
	v_add_f32_e32 v32, v32, v42
	v_lshlrev_b32_e32 v41, 16, v49
	v_and_b32_e32 v42, 0xffff0000, v49
	v_add_f32_e32 v32, v32, v41
	v_add_f32_e32 v32, v32, v42
	v_lshlrev_b32_e32 v41, 16, v50
	v_and_b32_e32 v42, 0xffff0000, v50
	v_add_f32_e32 v32, v32, v41
	v_add_f32_e32 v32, v32, v42
	v_lshlrev_b32_e32 v41, 16, v51
	v_and_b32_e32 v42, 0xffff0000, v51
	v_add_f32_e32 v32, v32, v41
	v_add_f32_e32 v32, v32, v42
	v_lshlrev_b32_e32 v41, 16, v52
	v_and_b32_e32 v42, 0xffff0000, v52
	v_add_f32_e32 v33, v41, v42
	v_lshlrev_b32_e32 v41, 16, v53
	v_and_b32_e32 v42, 0xffff0000, v53
	v_add_f32_e32 v33, v33, v41
	v_add_f32_e32 v33, v33, v42
	v_lshlrev_b32_e32 v41, 16, v54
	v_and_b32_e32 v42, 0xffff0000, v54
	v_add_f32_e32 v33, v33, v41
	v_add_f32_e32 v33, v33, v42
	v_lshlrev_b32_e32 v41, 16, v55
	v_and_b32_e32 v42, 0xffff0000, v55
	v_add_f32_e32 v33, v33, v41
	v_add_f32_e32 v33, v33, v42
	v_lshlrev_b32_e32 v41, 16, v56
	v_and_b32_e32 v42, 0xffff0000, v56
	v_add_f32_e32 v33, v33, v41
	v_add_f32_e32 v33, v33, v42
	v_lshlrev_b32_e32 v41, 16, v57
	v_and_b32_e32 v42, 0xffff0000, v57
	v_add_f32_e32 v33, v33, v41
	v_add_f32_e32 v33, v33, v42
	v_lshlrev_b32_e32 v41, 16, v58
	v_and_b32_e32 v42, 0xffff0000, v58
	v_add_f32_e32 v33, v33, v41
	v_add_f32_e32 v33, v33, v42
	v_lshlrev_b32_e32 v41, 16, v59
	v_and_b32_e32 v42, 0xffff0000, v59
	v_add_f32_e32 v33, v33, v41
	v_add_f32_e32 v33, v33, v42
	v_lshlrev_b32_e32 v41, 16, v60
	v_and_b32_e32 v42, 0xffff0000, v60
	v_add_f32_e32 v34, v41, v42
	v_lshlrev_b32_e32 v41, 16, v61
	v_and_b32_e32 v42, 0xffff0000, v61
	v_add_f32_e32 v34, v34, v41
	v_add_f32_e32 v34, v34, v42
	v_lshlrev_b32_e32 v41, 16, v62
	v_and_b32_e32 v42, 0xffff0000, v62
	v_add_f32_e32 v34, v34, v41
	v_add_f32_e32 v34, v34, v42
	v_lshlrev_b32_e32 v41, 16, v63
	v_and_b32_e32 v42, 0xffff0000, v63
	v_add_f32_e32 v34, v34, v41
	v_add_f32_e32 v34, v34, v42
	v_lshlrev_b32_e32 v41, 16, v64
	v_and_b32_e32 v42, 0xffff0000, v64
	v_add_f32_e32 v34, v34, v41
	v_add_f32_e32 v34, v34, v42
	v_lshlrev_b32_e32 v41, 16, v65
	v_and_b32_e32 v42, 0xffff0000, v65
	v_add_f32_e32 v34, v34, v41
	v_add_f32_e32 v34, v34, v42
	v_lshlrev_b32_e32 v41, 16, v66
	v_and_b32_e32 v42, 0xffff0000, v66
	v_add_f32_e32 v34, v34, v41
	v_add_f32_e32 v34, v34, v42
	v_lshlrev_b32_e32 v41, 16, v67
	v_and_b32_e32 v42, 0xffff0000, v67
	v_add_f32_e32 v34, v34, v41
	v_add_f32_e32 v34, v34, v42
	v_lshlrev_b32_e32 v41, 16, v68
	v_and_b32_e32 v42, 0xffff0000, v68
	v_add_f32_e32 v35, v41, v42
	v_lshlrev_b32_e32 v41, 16, v69
	v_and_b32_e32 v42, 0xffff0000, v69
	v_add_f32_e32 v35, v35, v41
	v_add_f32_e32 v35, v35, v42
	v_lshlrev_b32_e32 v41, 16, v70
	v_and_b32_e32 v42, 0xffff0000, v70
	v_add_f32_e32 v35, v35, v41
	v_add_f32_e32 v35, v35, v42
	v_lshlrev_b32_e32 v41, 16, v71
	v_and_b32_e32 v42, 0xffff0000, v71
	v_add_f32_e32 v35, v35, v41
	v_add_f32_e32 v35, v35, v42
	v_lshlrev_b32_e32 v41, 16, v72
	v_and_b32_e32 v42, 0xffff0000, v72
	v_add_f32_e32 v35, v35, v41
	v_add_f32_e32 v35, v35, v42
	v_lshlrev_b32_e32 v41, 16, v73
	v_and_b32_e32 v42, 0xffff0000, v73
	v_add_f32_e32 v35, v35, v41
	v_add_f32_e32 v35, v35, v42
	v_lshlrev_b32_e32 v41, 16, v74
	v_and_b32_e32 v42, 0xffff0000, v74
	v_add_f32_e32 v35, v35, v41
	v_add_f32_e32 v35, v35, v42
	v_lshlrev_b32_e32 v41, 16, v75
	v_and_b32_e32 v42, 0xffff0000, v75
	v_add_f32_e32 v35, v35, v41
	v_add_f32_e32 v35, v35, v42
	s_nop 1
	v_add_f32_dpp v32, v32, v32 quad_perm:[1,0,3,2] row_mask:0xf bank_mask:0xf
	v_add_f32_dpp v33, v33, v33 quad_perm:[1,0,3,2] row_mask:0xf bank_mask:0xf
	v_add_f32_dpp v34, v34, v34 quad_perm:[1,0,3,2] row_mask:0xf bank_mask:0xf
	v_add_f32_dpp v35, v35, v35 quad_perm:[1,0,3,2] row_mask:0xf bank_mask:0xf
	v_add_f32_dpp v32, v32, v32 quad_perm:[2,3,0,1] row_mask:0xf bank_mask:0xf
	v_add_f32_dpp v33, v33, v33 quad_perm:[2,3,0,1] row_mask:0xf bank_mask:0xf
	v_add_f32_dpp v34, v34, v34 quad_perm:[2,3,0,1] row_mask:0xf bank_mask:0xf
	v_add_f32_dpp v35, v35, v35 quad_perm:[2,3,0,1] row_mask:0xf bank_mask:0xf
	v_add_f32_dpp v32, v32, v32 row_half_mirror row_mask:0xf bank_mask:0xf
	v_add_f32_dpp v33, v33, v33 row_half_mirror row_mask:0xf bank_mask:0xf
	v_add_f32_dpp v34, v34, v34 row_half_mirror row_mask:0xf bank_mask:0xf
	v_add_f32_dpp v35, v35, v35 row_half_mirror row_mask:0xf bank_mask:0xf
	v_add_f32_dpp v32, v32, v32 row_mirror row_mask:0xf bank_mask:0xf
	v_add_f32_dpp v33, v33, v33 row_mirror row_mask:0xf bank_mask:0xf
	v_add_f32_dpp v34, v34, v34 row_mirror row_mask:0xf bank_mask:0xf
	v_add_f32_dpp v35, v35, v35 row_mirror row_mask:0xf bank_mask:0xf
	v_add_f32_dpp v32, v32, v32 row_bcast:15 row_mask:0xa bank_mask:0xf
	v_add_f32_dpp v33, v33, v33 row_bcast:15 row_mask:0xa bank_mask:0xf
	v_add_f32_dpp v34, v34, v34 row_bcast:15 row_mask:0xa bank_mask:0xf
	v_add_f32_dpp v35, v35, v35 row_bcast:15 row_mask:0xa bank_mask:0xf
	v_add_f32_dpp v32, v32, v32 row_bcast:31 row_mask:0xc bank_mask:0xf
	v_add_f32_dpp v33, v33, v33 row_bcast:31 row_mask:0xc bank_mask:0xf
	v_add_f32_dpp v34, v34, v34 row_bcast:31 row_mask:0xc bank_mask:0xf
	v_add_f32_dpp v35, v35, v35 row_bcast:31 row_mask:0xc bank_mask:0xf
; __device__ __forceinline__ void mixer_phase(LAS unsigned char* lds, bf16* U  , const bf16* V, const bf16* C, bf16* Bout,
;                                             const bf16* wsb, const float* sgu_b, const float* sgu_g, const bf16* pwT, const float* pool_scale, int G, int bid) {
;     ...
;                 float sm = 0.f;
; #pragma unroll
;                 for (int j = 0; j < 16; ++j) sm += x[j];
;                 const float mean = wave_sum(sm) * (1.f / D);
;                 float sq = 0.f;
; #pragma unroll
;                 for (int j = 0; j < 16; ++j) { const float d = x[j] - mean; sq += d * d; }
;                 const float rstd = 1.0f / sqrtf(wave_sum(sq) * (1.f / D) + EPS);
	v_mul_f32_e32 v32, 0x3a800000, v32
	v_mul_f32_e32 v33, 0x3a800000, v33
	v_mul_f32_e32 v34, 0x3a800000, v34
	v_mul_f32_e32 v35, 0x3a800000, v35
	s_nop 0
	v_readlane_b32 s56, v32, 63
	v_readlane_b32 s57, v33, 63
	v_readlane_b32 s58, v34, 63
	v_readlane_b32 s59, v35, 63
	s_nop 1
	v_mov_b32_e32 v36, 0
	v_lshlrev_b32_e32 v41, 16, v44
	v_and_b32_e32 v42, 0xffff0000, v44
	v_subrev_f32_e32 v41, s56, v41
	v_subrev_f32_e32 v42, s56, v42
	v_fmac_f32_e32 v36, v41, v41
	v_fmac_f32_e32 v36, v42, v42
	v_lshlrev_b32_e32 v41, 16, v45
	v_and_b32_e32 v42, 0xffff0000, v45
	v_subrev_f32_e32 v41, s56, v41
	v_subrev_f32_e32 v42, s56, v42
	v_fmac_f32_e32 v36, v41, v41
	v_fmac_f32_e32 v36, v42, v42
	v_lshlrev_b32_e32 v41, 16, v46
	v_and_b32_e32 v42, 0xffff0000, v46
	v_subrev_f32_e32 v41, s56, v41
	v_subrev_f32_e32 v42, s56, v42
	v_fmac_f32_e32 v36, v41, v41
	v_fmac_f32_e32 v36, v42, v42
	v_lshlrev_b32_e32 v41, 16, v47
	v_and_b32_e32 v42, 0xffff0000, v47
	v_subrev_f32_e32 v41, s56, v41
	v_subrev_f32_e32 v42, s56, v42
	v_fmac_f32_e32 v36, v41, v41
	v_fmac_f32_e32 v36, v42, v42
	v_lshlrev_b32_e32 v41, 16, v48
	v_and_b32_e32 v42, 0xffff0000, v48
	v_subrev_f32_e32 v41, s56, v41
	v_subrev_f32_e32 v42, s56, v42
	v_fmac_f32_e32 v36, v41, v41
	v_fmac_f32_e32 v36, v42, v42
	v_lshlrev_b32_e32 v41, 16, v49
	v_and_b32_e32 v42, 0xffff0000, v49
	v_subrev_f32_e32 v41, s56, v41
	v_subrev_f32_e32 v42, s56, v42
	v_fmac_f32_e32 v36, v41, v41
	v_fmac_f32_e32 v36, v42, v42
	v_lshlrev_b32_e32 v41, 16, v50
	v_and_b32_e32 v42, 0xffff0000, v50
	v_subrev_f32_e32 v41, s56, v41
	v_subrev_f32_e32 v42, s56, v42
	v_fmac_f32_e32 v36, v41, v41
	v_fmac_f32_e32 v36, v42, v42
	v_lshlrev_b32_e32 v41, 16, v51
	v_and_b32_e32 v42, 0xffff0000, v51
	v_subrev_f32_e32 v41, s56, v41
	v_subrev_f32_e32 v42, s56, v42
	v_fmac_f32_e32 v36, v41, v41
	v_fmac_f32_e32 v36, v42, v42
	v_mov_b32_e32 v37, 0
	v_lshlrev_b32_e32 v41, 16, v52
	v_and_b32_e32 v42, 0xffff0000, v52
	v_subrev_f32_e32 v41, s57, v41
	v_subrev_f32_e32 v42, s57, v42
	v_fmac_f32_e32 v37, v41, v41
	v_fmac_f32_e32 v37, v42, v42
	v_lshlrev_b32_e32 v41, 16, v53
	v_and_b32_e32 v42, 0xffff0000, v53
	v_subrev_f32_e32 v41, s57, v41
	v_subrev_f32_e32 v42, s57, v42
	v_fmac_f32_e32 v37, v41, v41
	v_fmac_f32_e32 v37, v42, v42
	v_lshlrev_b32_e32 v41, 16, v54
	v_and_b32_e32 v42, 0xffff0000, v54
	v_subrev_f32_e32 v41, s57, v41
	v_subrev_f32_e32 v42, s57, v42
	v_fmac_f32_e32 v37, v41, v41
	v_fmac_f32_e32 v37, v42, v42
	v_lshlrev_b32_e32 v41, 16, v55
	v_and_b32_e32 v42, 0xffff0000, v55
	v_subrev_f32_e32 v41, s57, v41
	v_subrev_f32_e32 v42, s57, v42
	v_fmac_f32_e32 v37, v41, v41
	v_fmac_f32_e32 v37, v42, v42
	v_lshlrev_b32_e32 v41, 16, v56
	v_and_b32_e32 v42, 0xffff0000, v56
	v_subrev_f32_e32 v41, s57, v41
	v_subrev_f32_e32 v42, s57, v42
	v_fmac_f32_e32 v37, v41, v41
	v_fmac_f32_e32 v37, v42, v42
	v_lshlrev_b32_e32 v41, 16, v57
	v_and_b32_e32 v42, 0xffff0000, v57
	v_subrev_f32_e32 v41, s57, v41
	v_subrev_f32_e32 v42, s57, v42
	v_fmac_f32_e32 v37, v41, v41
	v_fmac_f32_e32 v37, v42, v42
	v_lshlrev_b32_e32 v41, 16, v58
	v_and_b32_e32 v42, 0xffff0000, v58
	v_subrev_f32_e32 v41, s57, v41
	v_subrev_f32_e32 v42, s57, v42
	v_fmac_f32_e32 v37, v41, v41
	v_fmac_f32_e32 v37, v42, v42
	v_lshlrev_b32_e32 v41, 16, v59
	v_and_b32_e32 v42, 0xffff0000, v59
	v_subrev_f32_e32 v41, s57, v41
	v_subrev_f32_e32 v42, s57, v42
	v_fmac_f32_e32 v37, v41, v41
	v_fmac_f32_e32 v37, v42, v42
	v_mov_b32_e32 v38, 0
	v_lshlrev_b32_e32 v41, 16, v60
	v_and_b32_e32 v42, 0xffff0000, v60
	v_subrev_f32_e32 v41, s58, v41
	v_subrev_f32_e32 v42, s58, v42
	v_fmac_f32_e32 v38, v41, v41
	v_fmac_f32_e32 v38, v42, v42
	v_lshlrev_b32_e32 v41, 16, v61
	v_and_b32_e32 v42, 0xffff0000, v61
	v_subrev_f32_e32 v41, s58, v41
	v_subrev_f32_e32 v42, s58, v42
	v_fmac_f32_e32 v38, v41, v41
	v_fmac_f32_e32 v38, v42, v42
	v_lshlrev_b32_e32 v41, 16, v62
	v_and_b32_e32 v42, 0xffff0000, v62
	v_subrev_f32_e32 v41, s58, v41
	v_subrev_f32_e32 v42, s58, v42
	v_fmac_f32_e32 v38, v41, v41
	v_fmac_f32_e32 v38, v42, v42
	v_lshlrev_b32_e32 v41, 16, v63
	v_and_b32_e32 v42, 0xffff0000, v63
	v_subrev_f32_e32 v41, s58, v41
	v_subrev_f32_e32 v42, s58, v42
	v_fmac_f32_e32 v38, v41, v41
	v_fmac_f32_e32 v38, v42, v42
	v_lshlrev_b32_e32 v41, 16, v64
	v_and_b32_e32 v42, 0xffff0000, v64
	v_subrev_f32_e32 v41, s58, v41
	v_subrev_f32_e32 v42, s58, v42
	v_fmac_f32_e32 v38, v41, v41
	v_fmac_f32_e32 v38, v42, v42
	v_lshlrev_b32_e32 v41, 16, v65
	v_and_b32_e32 v42, 0xffff0000, v65
	v_subrev_f32_e32 v41, s58, v41
	v_subrev_f32_e32 v42, s58, v42
	v_fmac_f32_e32 v38, v41, v41
	v_fmac_f32_e32 v38, v42, v42
	v_lshlrev_b32_e32 v41, 16, v66
	v_and_b32_e32 v42, 0xffff0000, v66
	v_subrev_f32_e32 v41, s58, v41
	v_subrev_f32_e32 v42, s58, v42
	v_fmac_f32_e32 v38, v41, v41
	v_fmac_f32_e32 v38, v42, v42
	v_lshlrev_b32_e32 v41, 16, v67
	v_and_b32_e32 v42, 0xffff0000, v67
	v_subrev_f32_e32 v41, s58, v41
	v_subrev_f32_e32 v42, s58, v42
	v_fmac_f32_e32 v38, v41, v41
	v_fmac_f32_e32 v38, v42, v42
	v_mov_b32_e32 v39, 0
	v_lshlrev_b32_e32 v41, 16, v68
	v_and_b32_e32 v42, 0xffff0000, v68
	v_subrev_f32_e32 v41, s59, v41
	v_subrev_f32_e32 v42, s59, v42
	v_fmac_f32_e32 v39, v41, v41
	v_fmac_f32_e32 v39, v42, v42
	v_lshlrev_b32_e32 v41, 16, v69
	v_and_b32_e32 v42, 0xffff0000, v69
	v_subrev_f32_e32 v41, s59, v41
	v_subrev_f32_e32 v42, s59, v42
	v_fmac_f32_e32 v39, v41, v41
	v_fmac_f32_e32 v39, v42, v42
	v_lshlrev_b32_e32 v41, 16, v70
	v_and_b32_e32 v42, 0xffff0000, v70
	v_subrev_f32_e32 v41, s59, v41
	v_subrev_f32_e32 v42, s59, v42
	v_fmac_f32_e32 v39, v41, v41
	v_fmac_f32_e32 v39, v42, v42
	v_lshlrev_b32_e32 v41, 16, v71
	v_and_b32_e32 v42, 0xffff0000, v71
	v_subrev_f32_e32 v41, s59, v41
; __device__ __forceinline__ void mixer_phase(LAS unsigned char* lds, bf16* U  , const bf16* V, const bf16* C, bf16* Bout,
;                                             const bf16* wsb, const float* sgu_b, const float* sgu_g, const bf16* pwT, const float* pool_scale, int G, int bid) {
;     ...
;             for (int i = 0; i < 4; ++i) { const v4u* vr = (const v4u*)(V + (size_t)(r0 + wid * 16 + ib + i) * D); raw[i][0] = vr[lane]; raw[i][1] = vr[lane + 64]; }
;     ...
;                 float sq = 0.f;
; #pragma unroll
;                 for (int j = 0; j < 16; ++j) { const float d = x[j] - mean; sq += d * d; }
;                 const float rstd = 1.0f / sqrtf(wave_sum(sq) * (1.f / D) + EPS);
;                 if (lane == 0) { const int sr = wid * 16 + ib + i; stat[2 * sr] = mean; stat[2 * sr + 1] = rstd; }
	v_subrev_f32_e32 v42, s59, v42
	v_fmac_f32_e32 v39, v41, v41
	v_fmac_f32_e32 v39, v42, v42
	v_lshlrev_b32_e32 v41, 16, v72
	v_and_b32_e32 v42, 0xffff0000, v72
	v_subrev_f32_e32 v41, s59, v41
	v_subrev_f32_e32 v42, s59, v42
	v_fmac_f32_e32 v39, v41, v41
	v_fmac_f32_e32 v39, v42, v42
	v_lshlrev_b32_e32 v41, 16, v73
	v_and_b32_e32 v42, 0xffff0000, v73
	v_subrev_f32_e32 v41, s59, v41
	v_subrev_f32_e32 v42, s59, v42
	v_fmac_f32_e32 v39, v41, v41
	v_fmac_f32_e32 v39, v42, v42
	v_lshlrev_b32_e32 v41, 16, v74
	v_and_b32_e32 v42, 0xffff0000, v74
	v_subrev_f32_e32 v41, s59, v41
	v_subrev_f32_e32 v42, s59, v42
	v_fmac_f32_e32 v39, v41, v41
	v_fmac_f32_e32 v39, v42, v42
	v_lshlrev_b32_e32 v41, 16, v75
	v_and_b32_e32 v42, 0xffff0000, v75
	v_subrev_f32_e32 v41, s59, v41
	v_subrev_f32_e32 v42, s59, v42
	v_fmac_f32_e32 v39, v41, v41
	v_fmac_f32_e32 v39, v42, v42
	s_nop 1
	v_add_f32_dpp v36, v36, v36 quad_perm:[1,0,3,2] row_mask:0xf bank_mask:0xf
	v_add_f32_dpp v37, v37, v37 quad_perm:[1,0,3,2] row_mask:0xf bank_mask:0xf
	v_add_f32_dpp v38, v38, v38 quad_perm:[1,0,3,2] row_mask:0xf bank_mask:0xf
	v_add_f32_dpp v39, v39, v39 quad_perm:[1,0,3,2] row_mask:0xf bank_mask:0xf
	v_add_f32_dpp v36, v36, v36 quad_perm:[2,3,0,1] row_mask:0xf bank_mask:0xf
	v_add_f32_dpp v37, v37, v37 quad_perm:[2,3,0,1] row_mask:0xf bank_mask:0xf
	v_add_f32_dpp v38, v38, v38 quad_perm:[2,3,0,1] row_mask:0xf bank_mask:0xf
	v_add_f32_dpp v39, v39, v39 quad_perm:[2,3,0,1] row_mask:0xf bank_mask:0xf
	v_add_f32_dpp v36, v36, v36 row_half_mirror row_mask:0xf bank_mask:0xf
	v_add_f32_dpp v37, v37, v37 row_half_mirror row_mask:0xf bank_mask:0xf
	v_add_f32_dpp v38, v38, v38 row_half_mirror row_mask:0xf bank_mask:0xf
	v_add_f32_dpp v39, v39, v39 row_half_mirror row_mask:0xf bank_mask:0xf
	v_add_f32_dpp v36, v36, v36 row_mirror row_mask:0xf bank_mask:0xf
	v_add_f32_dpp v37, v37, v37 row_mirror row_mask:0xf bank_mask:0xf
	v_add_f32_dpp v38, v38, v38 row_mirror row_mask:0xf bank_mask:0xf
	v_add_f32_dpp v39, v39, v39 row_mirror row_mask:0xf bank_mask:0xf
	v_add_f32_dpp v36, v36, v36 row_bcast:15 row_mask:0xa bank_mask:0xf
	v_add_f32_dpp v37, v37, v37 row_bcast:15 row_mask:0xa bank_mask:0xf
	v_add_f32_dpp v38, v38, v38 row_bcast:15 row_mask:0xa bank_mask:0xf
	v_add_f32_dpp v39, v39, v39 row_bcast:15 row_mask:0xa bank_mask:0xf
	v_add_f32_dpp v36, v36, v36 row_bcast:31 row_mask:0xc bank_mask:0xf
	v_add_f32_dpp v37, v37, v37 row_bcast:31 row_mask:0xc bank_mask:0xf
	v_add_f32_dpp v38, v38, v38 row_bcast:31 row_mask:0xc bank_mask:0xf
	v_add_f32_dpp v39, v39, v39 row_bcast:31 row_mask:0xc bank_mask:0xf
	v_mul_f32_e32 v36, 0x3a800000, v36
	v_mul_f32_e32 v37, 0x3a800000, v37
	v_mul_f32_e32 v38, 0x3a800000, v38
	v_mul_f32_e32 v39, 0x3a800000, v39
	v_add_f32_e32 v36, 0x358637bd, v36
	v_add_f32_e32 v37, 0x358637bd, v37
	v_add_f32_e32 v38, 0x358637bd, v38
	v_add_f32_e32 v39, 0x358637bd, v39
	v_rsq_f32_e32 v36, v36
	v_rsq_f32_e32 v37, v37
	v_rsq_f32_e32 v38, v38
	v_rsq_f32_e32 v39, v39
	s_nop 0
	v_readlane_b32 s62, v36, 63
	v_readlane_b32 s63, v37, 63
	v_readlane_b32 s64, v38, 63
	v_readlane_b32 s65, v39, 63
	s_nop 3
	v_writelane_b32 v78, s56, 0
	v_writelane_b32 v79, s62, 0
	v_writelane_b32 v78, s57, 1
	v_writelane_b32 v79, s63, 1
	v_writelane_b32 v78, s58, 2
	v_writelane_b32 v79, s64, 2
	v_writelane_b32 v78, s59, 3
	v_writelane_b32 v79, s65, 3
	s_mov_b64 exec, 15
	ds_write_b64 v80, v[78:79] offset:32
	s_mov_b64 exec, -1
	s_add_u32 s24, s36, 12
	s_lshl_b32 s24, s24, 11
	v_add_u32_e32 v76, s24, v134
	v_add_u32_e32 v77, 0x1000, v76
	global_load_dwordx4 v[44:47], v76, s[12:13]
	global_load_dwordx4 v[48:51], v76, s[12:13] offset:1024
	global_load_dwordx4 v[52:55], v76, s[12:13] offset:2048
	global_load_dwordx4 v[56:59], v76, s[12:13] offset:3072
	global_load_dwordx4 v[60:63], v77, s[12:13]
	global_load_dwordx4 v[64:67], v77, s[12:13] offset:1024
	global_load_dwordx4 v[68:71], v77, s[12:13] offset:2048
	global_load_dwordx4 v[72:75], v77, s[12:13] offset:3072
	s_waitcnt vmcnt(8)
	v_lshlrev_b32_e32 v41, 16, v0
	v_and_b32_e32 v42, 0xffff0000, v0
	v_add_f32_e32 v32, v41, v42
	v_lshlrev_b32_e32 v41, 16, v1
	v_and_b32_e32 v42, 0xffff0000, v1
	v_add_f32_e32 v32, v32, v41
	v_add_f32_e32 v32, v32, v42
	v_lshlrev_b32_e32 v41, 16, v2
	v_and_b32_e32 v42, 0xffff0000, v2
	v_add_f32_e32 v32, v32, v41
	v_add_f32_e32 v32, v32, v42
	v_lshlrev_b32_e32 v41, 16, v3
	v_and_b32_e32 v42, 0xffff0000, v3
	v_add_f32_e32 v32, v32, v41
	v_add_f32_e32 v32, v32, v42
	v_lshlrev_b32_e32 v41, 16, v4
	v_and_b32_e32 v42, 0xffff0000, v4
	v_add_f32_e32 v32, v32, v41
	v_add_f32_e32 v32, v32, v42
	v_lshlrev_b32_e32 v41, 16, v5
	v_and_b32_e32 v42, 0xffff0000, v5
	v_add_f32_e32 v32, v32, v41
	v_add_f32_e32 v32, v32, v42
	v_lshlrev_b32_e32 v41, 16, v6
	v_and_b32_e32 v42, 0xffff0000, v6
	v_add_f32_e32 v32, v32, v41
	v_add_f32_e32 v32, v32, v42
	v_lshlrev_b32_e32 v41, 16, v7
	v_and_b32_e32 v42, 0xffff0000, v7
	v_add_f32_e32 v32, v32, v41
	v_add_f32_e32 v32, v32, v42
	v_lshlrev_b32_e32 v41, 16, v8
	v_and_b32_e32 v42, 0xffff0000, v8
	v_add_f32_e32 v33, v41, v42
	v_lshlrev_b32_e32 v41, 16, v9
	v_and_b32_e32 v42, 0xffff0000, v9
	v_add_f32_e32 v33, v33, v41
	v_add_f32_e32 v33, v33, v42
	v_lshlrev_b32_e32 v41, 16, v10
	v_and_b32_e32 v42, 0xffff0000, v10
	v_add_f32_e32 v33, v33, v41
	v_add_f32_e32 v33, v33, v42
	v_lshlrev_b32_e32 v41, 16, v11
	v_and_b32_e32 v42, 0xffff0000, v11
	v_add_f32_e32 v33, v33, v41
	v_add_f32_e32 v33, v33, v42
	v_lshlrev_b32_e32 v41, 16, v12
	v_and_b32_e32 v42, 0xffff0000, v12
	v_add_f32_e32 v33, v33, v41
	v_add_f32_e32 v33, v33, v42
	v_lshlrev_b32_e32 v41, 16, v13
	v_and_b32_e32 v42, 0xffff0000, v13
	v_add_f32_e32 v33, v33, v41
; __device__ __forceinline__ void unpack8(const v4u w, float (&x)[8]) { x[0] = bf_lo(w.x); x[1] = bf_hi(w.x); x[2] = bf_lo(w.y); x[3] = bf_hi(w.y); x[4] = bf_lo(w.z); x[5] = bf_hi(w.z); x[6] = bf_lo(w.w); x[7] = bf_hi(w.w); }
; __device__ __forceinline__ void mixer_phase(LAS unsigned char* lds, bf16* U  , const bf16* V, const bf16* C, bf16* Bout,
;                                             const bf16* wsb, const float* sgu_b, const float* sgu_g, const bf16* pwT, const float* pool_scale, int G, int bid) {
;     ...
;                 float x[16]; { float a[8], b[8]; unpack8(raw[i][0], a); unpack8(raw[i][1], b);
; #pragma unroll
;                     for (int j = 0; j < 8; ++j) { x[j] = a[j]; x[8 + j] = b[j]; } }
;                 float sm = 0.f;
; #pragma unroll
;                 for (int j = 0; j < 16; ++j) sm += x[j];
;                 const float mean = wave_sum(sm) * (1.f / D);
;                 float sq = 0.f;
; #pragma unroll
;                 for (int j = 0; j < 16; ++j) { const float d = x[j] - mean; sq += d * d; }
;                 const float rstd = 1.0f / sqrtf(wave_sum(sq) * (1.f / D) + EPS);
	v_add_f32_e32 v33, v33, v42
	v_lshlrev_b32_e32 v41, 16, v14
	v_and_b32_e32 v42, 0xffff0000, v14
	v_add_f32_e32 v33, v33, v41
	v_add_f32_e32 v33, v33, v42
	v_lshlrev_b32_e32 v41, 16, v15
	v_and_b32_e32 v42, 0xffff0000, v15
	v_add_f32_e32 v33, v33, v41
	v_add_f32_e32 v33, v33, v42
	v_lshlrev_b32_e32 v41, 16, v16
	v_and_b32_e32 v42, 0xffff0000, v16
	v_add_f32_e32 v34, v41, v42
	v_lshlrev_b32_e32 v41, 16, v17
	v_and_b32_e32 v42, 0xffff0000, v17
	v_add_f32_e32 v34, v34, v41
	v_add_f32_e32 v34, v34, v42
	v_lshlrev_b32_e32 v41, 16, v18
	v_and_b32_e32 v42, 0xffff0000, v18
	v_add_f32_e32 v34, v34, v41
	v_add_f32_e32 v34, v34, v42
	v_lshlrev_b32_e32 v41, 16, v19
	v_and_b32_e32 v42, 0xffff0000, v19
	v_add_f32_e32 v34, v34, v41
	v_add_f32_e32 v34, v34, v42
	v_lshlrev_b32_e32 v41, 16, v20
	v_and_b32_e32 v42, 0xffff0000, v20
	v_add_f32_e32 v34, v34, v41
	v_add_f32_e32 v34, v34, v42
	v_lshlrev_b32_e32 v41, 16, v21
	v_and_b32_e32 v42, 0xffff0000, v21
	v_add_f32_e32 v34, v34, v41
	v_add_f32_e32 v34, v34, v42
	v_lshlrev_b32_e32 v41, 16, v22
	v_and_b32_e32 v42, 0xffff0000, v22
	v_add_f32_e32 v34, v34, v41
	v_add_f32_e32 v34, v34, v42
	v_lshlrev_b32_e32 v41, 16, v23
	v_and_b32_e32 v42, 0xffff0000, v23
	v_add_f32_e32 v34, v34, v41
	v_add_f32_e32 v34, v34, v42
	v_lshlrev_b32_e32 v41, 16, v24
	v_and_b32_e32 v42, 0xffff0000, v24
	v_add_f32_e32 v35, v41, v42
	v_lshlrev_b32_e32 v41, 16, v25
	v_and_b32_e32 v42, 0xffff0000, v25
	v_add_f32_e32 v35, v35, v41
	v_add_f32_e32 v35, v35, v42
	v_lshlrev_b32_e32 v41, 16, v26
	v_and_b32_e32 v42, 0xffff0000, v26
	v_add_f32_e32 v35, v35, v41
	v_add_f32_e32 v35, v35, v42
	v_lshlrev_b32_e32 v41, 16, v27
	v_and_b32_e32 v42, 0xffff0000, v27
	v_add_f32_e32 v35, v35, v41
	v_add_f32_e32 v35, v35, v42
	v_lshlrev_b32_e32 v41, 16, v28
	v_and_b32_e32 v42, 0xffff0000, v28
	v_add_f32_e32 v35, v35, v41
	v_add_f32_e32 v35, v35, v42
	v_lshlrev_b32_e32 v41, 16, v29
	v_and_b32_e32 v42, 0xffff0000, v29
	v_add_f32_e32 v35, v35, v41
	v_add_f32_e32 v35, v35, v42
	v_lshlrev_b32_e32 v41, 16, v30
	v_and_b32_e32 v42, 0xffff0000, v30
	v_add_f32_e32 v35, v35, v41
	v_add_f32_e32 v35, v35, v42
	v_lshlrev_b32_e32 v41, 16, v31
	v_and_b32_e32 v42, 0xffff0000, v31
	v_add_f32_e32 v35, v35, v41
	v_add_f32_e32 v35, v35, v42
	s_nop 1
	v_add_f32_dpp v32, v32, v32 quad_perm:[1,0,3,2] row_mask:0xf bank_mask:0xf
	v_add_f32_dpp v33, v33, v33 quad_perm:[1,0,3,2] row_mask:0xf bank_mask:0xf
	v_add_f32_dpp v34, v34, v34 quad_perm:[1,0,3,2] row_mask:0xf bank_mask:0xf
	v_add_f32_dpp v35, v35, v35 quad_perm:[1,0,3,2] row_mask:0xf bank_mask:0xf
	v_add_f32_dpp v32, v32, v32 quad_perm:[2,3,0,1] row_mask:0xf bank_mask:0xf
	v_add_f32_dpp v33, v33, v33 quad_perm:[2,3,0,1] row_mask:0xf bank_mask:0xf
	v_add_f32_dpp v34, v34, v34 quad_perm:[2,3,0,1] row_mask:0xf bank_mask:0xf
	v_add_f32_dpp v35, v35, v35 quad_perm:[2,3,0,1] row_mask:0xf bank_mask:0xf
	v_add_f32_dpp v32, v32, v32 row_half_mirror row_mask:0xf bank_mask:0xf
	v_add_f32_dpp v33, v33, v33 row_half_mirror row_mask:0xf bank_mask:0xf
	v_add_f32_dpp v34, v34, v34 row_half_mirror row_mask:0xf bank_mask:0xf
	v_add_f32_dpp v35, v35, v35 row_half_mirror row_mask:0xf bank_mask:0xf
	v_add_f32_dpp v32, v32, v32 row_mirror row_mask:0xf bank_mask:0xf
	v_add_f32_dpp v33, v33, v33 row_mirror row_mask:0xf bank_mask:0xf
	v_add_f32_dpp v34, v34, v34 row_mirror row_mask:0xf bank_mask:0xf
	v_add_f32_dpp v35, v35, v35 row_mirror row_mask:0xf bank_mask:0xf
	v_add_f32_dpp v32, v32, v32 row_bcast:15 row_mask:0xa bank_mask:0xf
	v_add_f32_dpp v33, v33, v33 row_bcast:15 row_mask:0xa bank_mask:0xf
	v_add_f32_dpp v34, v34, v34 row_bcast:15 row_mask:0xa bank_mask:0xf
	v_add_f32_dpp v35, v35, v35 row_bcast:15 row_mask:0xa bank_mask:0xf
	v_add_f32_dpp v32, v32, v32 row_bcast:31 row_mask:0xc bank_mask:0xf
	v_add_f32_dpp v33, v33, v33 row_bcast:31 row_mask:0xc bank_mask:0xf
	v_add_f32_dpp v34, v34, v34 row_bcast:31 row_mask:0xc bank_mask:0xf
	v_add_f32_dpp v35, v35, v35 row_bcast:31 row_mask:0xc bank_mask:0xf
	v_mul_f32_e32 v32, 0x3a800000, v32
	v_mul_f32_e32 v33, 0x3a800000, v33
	v_mul_f32_e32 v34, 0x3a800000, v34
	v_mul_f32_e32 v35, 0x3a800000, v35
	s_nop 0
	v_readlane_b32 s56, v32, 63
	v_readlane_b32 s57, v33, 63
	v_readlane_b32 s58, v34, 63
	v_readlane_b32 s59, v35, 63
	s_nop 1
	v_mov_b32_e32 v36, 0
	v_lshlrev_b32_e32 v41, 16, v0
	v_and_b32_e32 v42, 0xffff0000, v0
	v_subrev_f32_e32 v41, s56, v41
	v_subrev_f32_e32 v42, s56, v42
	v_fmac_f32_e32 v36, v41, v41
	v_fmac_f32_e32 v36, v42, v42
	v_lshlrev_b32_e32 v41, 16, v1
	v_and_b32_e32 v42, 0xffff0000, v1
	v_subrev_f32_e32 v41, s56, v41
	v_subrev_f32_e32 v42, s56, v42
	v_fmac_f32_e32 v36, v41, v41
	v_fmac_f32_e32 v36, v42, v42
	v_lshlrev_b32_e32 v41, 16, v2
	v_and_b32_e32 v42, 0xffff0000, v2
	v_subrev_f32_e32 v41, s56, v41
	v_subrev_f32_e32 v42, s56, v42
	v_fmac_f32_e32 v36, v41, v41
	v_fmac_f32_e32 v36, v42, v42
	v_lshlrev_b32_e32 v41, 16, v3
	v_and_b32_e32 v42, 0xffff0000, v3
	v_subrev_f32_e32 v41, s56, v41
	v_subrev_f32_e32 v42, s56, v42
	v_fmac_f32_e32 v36, v41, v41
	v_fmac_f32_e32 v36, v42, v42
	v_lshlrev_b32_e32 v41, 16, v4
	v_and_b32_e32 v42, 0xffff0000, v4
	v_subrev_f32_e32 v41, s56, v41
	v_subrev_f32_e32 v42, s56, v42
	v_fmac_f32_e32 v36, v41, v41
	v_fmac_f32_e32 v36, v42, v42
	v_lshlrev_b32_e32 v41, 16, v5
	v_and_b32_e32 v42, 0xffff0000, v5
	v_subrev_f32_e32 v41, s56, v41
	v_subrev_f32_e32 v42, s56, v42
	v_fmac_f32_e32 v36, v41, v41
	v_fmac_f32_e32 v36, v42, v42
	v_lshlrev_b32_e32 v41, 16, v6
	v_and_b32_e32 v42, 0xffff0000, v6
	v_subrev_f32_e32 v41, s56, v41
	v_subrev_f32_e32 v42, s56, v42
	v_fmac_f32_e32 v36, v41, v41
	v_fmac_f32_e32 v36, v42, v42
	v_lshlrev_b32_e32 v41, 16, v7
; __device__ __forceinline__ void mixer_phase(LAS unsigned char* lds, bf16* U  , const bf16* V, const bf16* C, bf16* Bout,
;                                             const bf16* wsb, const float* sgu_b, const float* sgu_g, const bf16* pwT, const float* pool_scale, int G, int bid) {
;     ...
;                 float sq = 0.f;
; #pragma unroll
;                 for (int j = 0; j < 16; ++j) { const float d = x[j] - mean; sq += d * d; }
	v_and_b32_e32 v42, 0xffff0000, v7
	v_subrev_f32_e32 v41, s56, v41
	v_subrev_f32_e32 v42, s56, v42
	v_fmac_f32_e32 v36, v41, v41
	v_fmac_f32_e32 v36, v42, v42
	v_mov_b32_e32 v37, 0
	v_lshlrev_b32_e32 v41, 16, v8
	v_and_b32_e32 v42, 0xffff0000, v8
	v_subrev_f32_e32 v41, s57, v41
	v_subrev_f32_e32 v42, s57, v42
	v_fmac_f32_e32 v37, v41, v41
	v_fmac_f32_e32 v37, v42, v42
	v_lshlrev_b32_e32 v41, 16, v9
	v_and_b32_e32 v42, 0xffff0000, v9
	v_subrev_f32_e32 v41, s57, v41
	v_subrev_f32_e32 v42, s57, v42
	v_fmac_f32_e32 v37, v41, v41
	v_fmac_f32_e32 v37, v42, v42
	v_lshlrev_b32_e32 v41, 16, v10
	v_and_b32_e32 v42, 0xffff0000, v10
	v_subrev_f32_e32 v41, s57, v41
	v_subrev_f32_e32 v42, s57, v42
	v_fmac_f32_e32 v37, v41, v41
	v_fmac_f32_e32 v37, v42, v42
	v_lshlrev_b32_e32 v41, 16, v11
	v_and_b32_e32 v42, 0xffff0000, v11
	v_subrev_f32_e32 v41, s57, v41
	v_subrev_f32_e32 v42, s57, v42
	v_fmac_f32_e32 v37, v41, v41
	v_fmac_f32_e32 v37, v42, v42
	v_lshlrev_b32_e32 v41, 16, v12
	v_and_b32_e32 v42, 0xffff0000, v12
	v_subrev_f32_e32 v41, s57, v41
	v_subrev_f32_e32 v42, s57, v42
	v_fmac_f32_e32 v37, v41, v41
	v_fmac_f32_e32 v37, v42, v42
	v_lshlrev_b32_e32 v41, 16, v13
	v_and_b32_e32 v42, 0xffff0000, v13
	v_subrev_f32_e32 v41, s57, v41
	v_subrev_f32_e32 v42, s57, v42
	v_fmac_f32_e32 v37, v41, v41
	v_fmac_f32_e32 v37, v42, v42
	v_lshlrev_b32_e32 v41, 16, v14
	v_and_b32_e32 v42, 0xffff0000, v14
	v_subrev_f32_e32 v41, s57, v41
	v_subrev_f32_e32 v42, s57, v42
	v_fmac_f32_e32 v37, v41, v41
	v_fmac_f32_e32 v37, v42, v42
	v_lshlrev_b32_e32 v41, 16, v15
	v_and_b32_e32 v42, 0xffff0000, v15
	v_subrev_f32_e32 v41, s57, v41
	v_subrev_f32_e32 v42, s57, v42
	v_fmac_f32_e32 v37, v41, v41
	v_fmac_f32_e32 v37, v42, v42
	v_mov_b32_e32 v38, 0
	v_lshlrev_b32_e32 v41, 16, v16
	v_and_b32_e32 v42, 0xffff0000, v16
	v_subrev_f32_e32 v41, s58, v41
	v_subrev_f32_e32 v42, s58, v42
	v_fmac_f32_e32 v38, v41, v41
	v_fmac_f32_e32 v38, v42, v42
	v_lshlrev_b32_e32 v41, 16, v17
	v_and_b32_e32 v42, 0xffff0000, v17
	v_subrev_f32_e32 v41, s58, v41
	v_subrev_f32_e32 v42, s58, v42
	v_fmac_f32_e32 v38, v41, v41
	v_fmac_f32_e32 v38, v42, v42
	v_lshlrev_b32_e32 v41, 16, v18
	v_and_b32_e32 v42, 0xffff0000, v18
	v_subrev_f32_e32 v41, s58, v41
	v_subrev_f32_e32 v42, s58, v42
	v_fmac_f32_e32 v38, v41, v41
	v_fmac_f32_e32 v38, v42, v42
	v_lshlrev_b32_e32 v41, 16, v19
	v_and_b32_e32 v42, 0xffff0000, v19
	v_subrev_f32_e32 v41, s58, v41
	v_subrev_f32_e32 v42, s58, v42
	v_fmac_f32_e32 v38, v41, v41
	v_fmac_f32_e32 v38, v42, v42
	v_lshlrev_b32_e32 v41, 16, v20
	v_and_b32_e32 v42, 0xffff0000, v20
	v_subrev_f32_e32 v41, s58, v41
	v_subrev_f32_e32 v42, s58, v42
	v_fmac_f32_e32 v38, v41, v41
	v_fmac_f32_e32 v38, v42, v42
	v_lshlrev_b32_e32 v41, 16, v21
	v_and_b32_e32 v42, 0xffff0000, v21
	v_subrev_f32_e32 v41, s58, v41
	v_subrev_f32_e32 v42, s58, v42
	v_fmac_f32_e32 v38, v41, v41
	v_fmac_f32_e32 v38, v42, v42
	v_lshlrev_b32_e32 v41, 16, v22
	v_and_b32_e32 v42, 0xffff0000, v22
	v_subrev_f32_e32 v41, s58, v41
	v_subrev_f32_e32 v42, s58, v42
	v_fmac_f32_e32 v38, v41, v41
	v_fmac_f32_e32 v38, v42, v42
	v_lshlrev_b32_e32 v41, 16, v23
	v_and_b32_e32 v42, 0xffff0000, v23
	v_subrev_f32_e32 v41, s58, v41
	v_subrev_f32_e32 v42, s58, v42
	v_fmac_f32_e32 v38, v41, v41
	v_fmac_f32_e32 v38, v42, v42
	v_mov_b32_e32 v39, 0
	v_lshlrev_b32_e32 v41, 16, v24
	v_and_b32_e32 v42, 0xffff0000, v24
	v_subrev_f32_e32 v41, s59, v41
	v_subrev_f32_e32 v42, s59, v42
	v_fmac_f32_e32 v39, v41, v41
	v_fmac_f32_e32 v39, v42, v42
	v_lshlrev_b32_e32 v41, 16, v25
	v_and_b32_e32 v42, 0xffff0000, v25
	v_subrev_f32_e32 v41, s59, v41
	v_subrev_f32_e32 v42, s59, v42
	v_fmac_f32_e32 v39, v41, v41
	v_fmac_f32_e32 v39, v42, v42
	v_lshlrev_b32_e32 v41, 16, v26
	v_and_b32_e32 v42, 0xffff0000, v26
	v_subrev_f32_e32 v41, s59, v41
	v_subrev_f32_e32 v42, s59, v42
	v_fmac_f32_e32 v39, v41, v41
	v_fmac_f32_e32 v39, v42, v42
	v_lshlrev_b32_e32 v41, 16, v27
	v_and_b32_e32 v42, 0xffff0000, v27
	v_subrev_f32_e32 v41, s59, v41
	v_subrev_f32_e32 v42, s59, v42
	v_fmac_f32_e32 v39, v41, v41
	v_fmac_f32_e32 v39, v42, v42
	v_lshlrev_b32_e32 v41, 16, v28
	v_and_b32_e32 v42, 0xffff0000, v28
	v_subrev_f32_e32 v41, s59, v41
	v_subrev_f32_e32 v42, s59, v42
	v_fmac_f32_e32 v39, v41, v41
	v_fmac_f32_e32 v39, v42, v42
	v_lshlrev_b32_e32 v41, 16, v29
	v_and_b32_e32 v42, 0xffff0000, v29
	v_subrev_f32_e32 v41, s59, v41
	v_subrev_f32_e32 v42, s59, v42
	v_fmac_f32_e32 v39, v41, v41
	v_fmac_f32_e32 v39, v42, v42
	v_lshlrev_b32_e32 v41, 16, v30
	v_and_b32_e32 v42, 0xffff0000, v30
	v_subrev_f32_e32 v41, s59, v41
	v_subrev_f32_e32 v42, s59, v42
	v_fmac_f32_e32 v39, v41, v41
	v_fmac_f32_e32 v39, v42, v42
	v_lshlrev_b32_e32 v41, 16, v31
	v_and_b32_e32 v42, 0xffff0000, v31
	v_subrev_f32_e32 v41, s59, v41
	v_subrev_f32_e32 v42, s59, v42
	v_fmac_f32_e32 v39, v41, v41
	v_fmac_f32_e32 v39, v42, v42
	s_nop 1
	v_add_f32_dpp v36, v36, v36 quad_perm:[1,0,3,2] row_mask:0xf bank_mask:0xf
	v_add_f32_dpp v37, v37, v37 quad_perm:[1,0,3,2] row_mask:0xf bank_mask:0xf
	v_add_f32_dpp v38, v38, v38 quad_perm:[1,0,3,2] row_mask:0xf bank_mask:0xf
	v_add_f32_dpp v39, v39, v39 quad_perm:[1,0,3,2] row_mask:0xf bank_mask:0xf
	v_add_f32_dpp v36, v36, v36 quad_perm:[2,3,0,1] row_mask:0xf bank_mask:0xf
	v_add_f32_dpp v37, v37, v37 quad_perm:[2,3,0,1] row_mask:0xf bank_mask:0xf
	v_add_f32_dpp v38, v38, v38 quad_perm:[2,3,0,1] row_mask:0xf bank_mask:0xf
	v_add_f32_dpp v39, v39, v39 quad_perm:[2,3,0,1] row_mask:0xf bank_mask:0xf
	v_add_f32_dpp v36, v36, v36 row_half_mirror row_mask:0xf bank_mask:0xf
	v_add_f32_dpp v37, v37, v37 row_half_mirror row_mask:0xf bank_mask:0xf
	v_add_f32_dpp v38, v38, v38 row_half_mirror row_mask:0xf bank_mask:0xf
; __device__ __forceinline__ void unpack8(const v4u w, float (&x)[8]) { x[0] = bf_lo(w.x); x[1] = bf_hi(w.x); x[2] = bf_lo(w.y); x[3] = bf_hi(w.y); x[4] = bf_lo(w.z); x[5] = bf_hi(w.z); x[6] = bf_lo(w.w); x[7] = bf_hi(w.w); }
; __device__ __forceinline__ void mixer_phase(LAS unsigned char* lds, bf16* U  , const bf16* V, const bf16* C, bf16* Bout,
;                                             const bf16* wsb, const float* sgu_b, const float* sgu_g, const bf16* pwT, const float* pool_scale, int G, int bid) {
;     ...
;                 float x[16]; { float a[8], b[8]; unpack8(raw[i][0], a); unpack8(raw[i][1], b);
; #pragma unroll
;                     for (int j = 0; j < 8; ++j) { x[j] = a[j]; x[8 + j] = b[j]; } }
;                 float sm = 0.f;
; #pragma unroll
;                 for (int j = 0; j < 16; ++j) sm += x[j];
;                 const float mean = wave_sum(sm) * (1.f / D);
;                 float sq = 0.f;
; #pragma unroll
;                 for (int j = 0; j < 16; ++j) { const float d = x[j] - mean; sq += d * d; }
;                 const float rstd = 1.0f / sqrtf(wave_sum(sq) * (1.f / D) + EPS);
;                 if (lane == 0) { const int sr = wid * 16 + ib + i; stat[2 * sr] = mean; stat[2 * sr + 1] = rstd; }
	v_add_f32_dpp v39, v39, v39 row_half_mirror row_mask:0xf bank_mask:0xf
	v_add_f32_dpp v36, v36, v36 row_mirror row_mask:0xf bank_mask:0xf
	v_add_f32_dpp v37, v37, v37 row_mirror row_mask:0xf bank_mask:0xf
	v_add_f32_dpp v38, v38, v38 row_mirror row_mask:0xf bank_mask:0xf
	v_add_f32_dpp v39, v39, v39 row_mirror row_mask:0xf bank_mask:0xf
	v_add_f32_dpp v36, v36, v36 row_bcast:15 row_mask:0xa bank_mask:0xf
	v_add_f32_dpp v37, v37, v37 row_bcast:15 row_mask:0xa bank_mask:0xf
	v_add_f32_dpp v38, v38, v38 row_bcast:15 row_mask:0xa bank_mask:0xf
	v_add_f32_dpp v39, v39, v39 row_bcast:15 row_mask:0xa bank_mask:0xf
	v_add_f32_dpp v36, v36, v36 row_bcast:31 row_mask:0xc bank_mask:0xf
	v_add_f32_dpp v37, v37, v37 row_bcast:31 row_mask:0xc bank_mask:0xf
	v_add_f32_dpp v38, v38, v38 row_bcast:31 row_mask:0xc bank_mask:0xf
	v_add_f32_dpp v39, v39, v39 row_bcast:31 row_mask:0xc bank_mask:0xf
	v_mul_f32_e32 v36, 0x3a800000, v36
	v_mul_f32_e32 v37, 0x3a800000, v37
	v_mul_f32_e32 v38, 0x3a800000, v38
	v_mul_f32_e32 v39, 0x3a800000, v39
	v_add_f32_e32 v36, 0x358637bd, v36
	v_add_f32_e32 v37, 0x358637bd, v37
	v_add_f32_e32 v38, 0x358637bd, v38
	v_add_f32_e32 v39, 0x358637bd, v39
	v_rsq_f32_e32 v36, v36
	v_rsq_f32_e32 v37, v37
	v_rsq_f32_e32 v38, v38
	v_rsq_f32_e32 v39, v39
	s_nop 0
	v_readlane_b32 s62, v36, 63
	v_readlane_b32 s63, v37, 63
	v_readlane_b32 s64, v38, 63
	v_readlane_b32 s65, v39, 63
	s_nop 3
	v_writelane_b32 v78, s56, 0
	v_writelane_b32 v79, s62, 0
	v_writelane_b32 v78, s57, 1
	v_writelane_b32 v79, s63, 1
	v_writelane_b32 v78, s58, 2
	v_writelane_b32 v79, s64, 2
	v_writelane_b32 v78, s59, 3
	v_writelane_b32 v79, s65, 3
	s_mov_b64 exec, 15
	ds_write_b64 v80, v[78:79] offset:64
	s_mov_b64 exec, -1
	s_waitcnt vmcnt(0)
	v_lshlrev_b32_e32 v41, 16, v44
	v_and_b32_e32 v42, 0xffff0000, v44
	v_add_f32_e32 v32, v41, v42
	v_lshlrev_b32_e32 v41, 16, v45
	v_and_b32_e32 v42, 0xffff0000, v45
	v_add_f32_e32 v32, v32, v41
	v_add_f32_e32 v32, v32, v42
	v_lshlrev_b32_e32 v41, 16, v46
	v_and_b32_e32 v42, 0xffff0000, v46
	v_add_f32_e32 v32, v32, v41
	v_add_f32_e32 v32, v32, v42
	v_lshlrev_b32_e32 v41, 16, v47
	v_and_b32_e32 v42, 0xffff0000, v47
	v_add_f32_e32 v32, v32, v41
	v_add_f32_e32 v32, v32, v42
	v_lshlrev_b32_e32 v41, 16, v48
	v_and_b32_e32 v42, 0xffff0000, v48
	v_add_f32_e32 v32, v32, v41
	v_add_f32_e32 v32, v32, v42
	v_lshlrev_b32_e32 v41, 16, v49
	v_and_b32_e32 v42, 0xffff0000, v49
	v_add_f32_e32 v32, v32, v41
	v_add_f32_e32 v32, v32, v42
	v_lshlrev_b32_e32 v41, 16, v50
	v_and_b32_e32 v42, 0xffff0000, v50
	v_add_f32_e32 v32, v32, v41
	v_add_f32_e32 v32, v32, v42
	v_lshlrev_b32_e32 v41, 16, v51
	v_and_b32_e32 v42, 0xffff0000, v51
	v_add_f32_e32 v32, v32, v41
	v_add_f32_e32 v32, v32, v42
	v_lshlrev_b32_e32 v41, 16, v52
	v_and_b32_e32 v42, 0xffff0000, v52
	v_add_f32_e32 v33, v41, v42
	v_lshlrev_b32_e32 v41, 16, v53
	v_and_b32_e32 v42, 0xffff0000, v53
	v_add_f32_e32 v33, v33, v41
	v_add_f32_e32 v33, v33, v42
	v_lshlrev_b32_e32 v41, 16, v54
	v_and_b32_e32 v42, 0xffff0000, v54
	v_add_f32_e32 v33, v33, v41
	v_add_f32_e32 v33, v33, v42
	v_lshlrev_b32_e32 v41, 16, v55
	v_and_b32_e32 v42, 0xffff0000, v55
	v_add_f32_e32 v33, v33, v41
	v_add_f32_e32 v33, v33, v42
	v_lshlrev_b32_e32 v41, 16, v56
	v_and_b32_e32 v42, 0xffff0000, v56
	v_add_f32_e32 v33, v33, v41
	v_add_f32_e32 v33, v33, v42
	v_lshlrev_b32_e32 v41, 16, v57
	v_and_b32_e32 v42, 0xffff0000, v57
	v_add_f32_e32 v33, v33, v41
	v_add_f32_e32 v33, v33, v42
	v_lshlrev_b32_e32 v41, 16, v58
	v_and_b32_e32 v42, 0xffff0000, v58
	v_add_f32_e32 v33, v33, v41
	v_add_f32_e32 v33, v33, v42
	v_lshlrev_b32_e32 v41, 16, v59
	v_and_b32_e32 v42, 0xffff0000, v59
	v_add_f32_e32 v33, v33, v41
	v_add_f32_e32 v33, v33, v42
	v_lshlrev_b32_e32 v41, 16, v60
	v_and_b32_e32 v42, 0xffff0000, v60
	v_add_f32_e32 v34, v41, v42
	v_lshlrev_b32_e32 v41, 16, v61
	v_and_b32_e32 v42, 0xffff0000, v61
	v_add_f32_e32 v34, v34, v41
	v_add_f32_e32 v34, v34, v42
	v_lshlrev_b32_e32 v41, 16, v62
	v_and_b32_e32 v42, 0xffff0000, v62
	v_add_f32_e32 v34, v34, v41
	v_add_f32_e32 v34, v34, v42
	v_lshlrev_b32_e32 v41, 16, v63
	v_and_b32_e32 v42, 0xffff0000, v63
	v_add_f32_e32 v34, v34, v41
	v_add_f32_e32 v34, v34, v42
	v_lshlrev_b32_e32 v41, 16, v64
	v_and_b32_e32 v42, 0xffff0000, v64
	v_add_f32_e32 v34, v34, v41
	v_add_f32_e32 v34, v34, v42
	v_lshlrev_b32_e32 v41, 16, v65
	v_and_b32_e32 v42, 0xffff0000, v65
	v_add_f32_e32 v34, v34, v41
	v_add_f32_e32 v34, v34, v42
	v_lshlrev_b32_e32 v41, 16, v66
	v_and_b32_e32 v42, 0xffff0000, v66
	v_add_f32_e32 v34, v34, v41
	v_add_f32_e32 v34, v34, v42
	v_lshlrev_b32_e32 v41, 16, v67
	v_and_b32_e32 v42, 0xffff0000, v67
	v_add_f32_e32 v34, v34, v41
	v_add_f32_e32 v34, v34, v42
	v_lshlrev_b32_e32 v41, 16, v68
	v_and_b32_e32 v42, 0xffff0000, v68
	v_add_f32_e32 v35, v41, v42
	v_lshlrev_b32_e32 v41, 16, v69
	v_and_b32_e32 v42, 0xffff0000, v69
	v_add_f32_e32 v35, v35, v41
	v_add_f32_e32 v35, v35, v42
	v_lshlrev_b32_e32 v41, 16, v70
	v_and_b32_e32 v42, 0xffff0000, v70
	v_add_f32_e32 v35, v35, v41
	v_add_f32_e32 v35, v35, v42
	v_lshlrev_b32_e32 v41, 16, v71
	v_and_b32_e32 v42, 0xffff0000, v71
	v_add_f32_e32 v35, v35, v41
	v_add_f32_e32 v35, v35, v42
	v_lshlrev_b32_e32 v41, 16, v72
	v_and_b32_e32 v42, 0xffff0000, v72
	v_add_f32_e32 v35, v35, v41
	v_add_f32_e32 v35, v35, v42
	v_lshlrev_b32_e32 v41, 16, v73
	v_and_b32_e32 v42, 0xffff0000, v73
	v_add_f32_e32 v35, v35, v41
	v_add_f32_e32 v35, v35, v42
	v_lshlrev_b32_e32 v41, 16, v74
	v_and_b32_e32 v42, 0xffff0000, v74
	v_add_f32_e32 v35, v35, v41
	v_add_f32_e32 v35, v35, v42
	v_lshlrev_b32_e32 v41, 16, v75
	v_and_b32_e32 v42, 0xffff0000, v75
	v_add_f32_e32 v35, v35, v41
; __device__ __forceinline__ void mixer_phase(LAS unsigned char* lds, bf16* U  , const bf16* V, const bf16* C, bf16* Bout,
;                                             const bf16* wsb, const float* sgu_b, const float* sgu_g, const bf16* pwT, const float* pool_scale, int G, int bid) {
;     ...
; #pragma unroll
;                 for (int j = 0; j < 16; ++j) sm += x[j];
;                 const float mean = wave_sum(sm) * (1.f / D);
;                 float sq = 0.f;
; #pragma unroll
;                 for (int j = 0; j < 16; ++j) { const float d = x[j] - mean; sq += d * d; }
	v_add_f32_e32 v35, v35, v42
	s_nop 1
	v_add_f32_dpp v32, v32, v32 quad_perm:[1,0,3,2] row_mask:0xf bank_mask:0xf
	v_add_f32_dpp v33, v33, v33 quad_perm:[1,0,3,2] row_mask:0xf bank_mask:0xf
	v_add_f32_dpp v34, v34, v34 quad_perm:[1,0,3,2] row_mask:0xf bank_mask:0xf
	v_add_f32_dpp v35, v35, v35 quad_perm:[1,0,3,2] row_mask:0xf bank_mask:0xf
	v_add_f32_dpp v32, v32, v32 quad_perm:[2,3,0,1] row_mask:0xf bank_mask:0xf
	v_add_f32_dpp v33, v33, v33 quad_perm:[2,3,0,1] row_mask:0xf bank_mask:0xf
	v_add_f32_dpp v34, v34, v34 quad_perm:[2,3,0,1] row_mask:0xf bank_mask:0xf
	v_add_f32_dpp v35, v35, v35 quad_perm:[2,3,0,1] row_mask:0xf bank_mask:0xf
	v_add_f32_dpp v32, v32, v32 row_half_mirror row_mask:0xf bank_mask:0xf
	v_add_f32_dpp v33, v33, v33 row_half_mirror row_mask:0xf bank_mask:0xf
	v_add_f32_dpp v34, v34, v34 row_half_mirror row_mask:0xf bank_mask:0xf
	v_add_f32_dpp v35, v35, v35 row_half_mirror row_mask:0xf bank_mask:0xf
	v_add_f32_dpp v32, v32, v32 row_mirror row_mask:0xf bank_mask:0xf
	v_add_f32_dpp v33, v33, v33 row_mirror row_mask:0xf bank_mask:0xf
	v_add_f32_dpp v34, v34, v34 row_mirror row_mask:0xf bank_mask:0xf
	v_add_f32_dpp v35, v35, v35 row_mirror row_mask:0xf bank_mask:0xf
	v_add_f32_dpp v32, v32, v32 row_bcast:15 row_mask:0xa bank_mask:0xf
	v_add_f32_dpp v33, v33, v33 row_bcast:15 row_mask:0xa bank_mask:0xf
	v_add_f32_dpp v34, v34, v34 row_bcast:15 row_mask:0xa bank_mask:0xf
	v_add_f32_dpp v35, v35, v35 row_bcast:15 row_mask:0xa bank_mask:0xf
	v_add_f32_dpp v32, v32, v32 row_bcast:31 row_mask:0xc bank_mask:0xf
	v_add_f32_dpp v33, v33, v33 row_bcast:31 row_mask:0xc bank_mask:0xf
	v_add_f32_dpp v34, v34, v34 row_bcast:31 row_mask:0xc bank_mask:0xf
	v_add_f32_dpp v35, v35, v35 row_bcast:31 row_mask:0xc bank_mask:0xf
	v_mul_f32_e32 v32, 0x3a800000, v32
	v_mul_f32_e32 v33, 0x3a800000, v33
	v_mul_f32_e32 v34, 0x3a800000, v34
	v_mul_f32_e32 v35, 0x3a800000, v35
	s_nop 0
	v_readlane_b32 s56, v32, 63
	v_readlane_b32 s57, v33, 63
	v_readlane_b32 s58, v34, 63
	v_readlane_b32 s59, v35, 63
	s_nop 1
	v_mov_b32_e32 v36, 0
	v_lshlrev_b32_e32 v41, 16, v44
	v_and_b32_e32 v42, 0xffff0000, v44
	v_subrev_f32_e32 v41, s56, v41
	v_subrev_f32_e32 v42, s56, v42
	v_fmac_f32_e32 v36, v41, v41
	v_fmac_f32_e32 v36, v42, v42
	v_lshlrev_b32_e32 v41, 16, v45
	v_and_b32_e32 v42, 0xffff0000, v45
	v_subrev_f32_e32 v41, s56, v41
	v_subrev_f32_e32 v42, s56, v42
	v_fmac_f32_e32 v36, v41, v41
	v_fmac_f32_e32 v36, v42, v42
	v_lshlrev_b32_e32 v41, 16, v46
	v_and_b32_e32 v42, 0xffff0000, v46
	v_subrev_f32_e32 v41, s56, v41
	v_subrev_f32_e32 v42, s56, v42
	v_fmac_f32_e32 v36, v41, v41
	v_fmac_f32_e32 v36, v42, v42
	v_lshlrev_b32_e32 v41, 16, v47
	v_and_b32_e32 v42, 0xffff0000, v47
	v_subrev_f32_e32 v41, s56, v41
	v_subrev_f32_e32 v42, s56, v42
	v_fmac_f32_e32 v36, v41, v41
	v_fmac_f32_e32 v36, v42, v42
	v_lshlrev_b32_e32 v41, 16, v48
	v_and_b32_e32 v42, 0xffff0000, v48
	v_subrev_f32_e32 v41, s56, v41
	v_subrev_f32_e32 v42, s56, v42
	v_fmac_f32_e32 v36, v41, v41
	v_fmac_f32_e32 v36, v42, v42
	v_lshlrev_b32_e32 v41, 16, v49
	v_and_b32_e32 v42, 0xffff0000, v49
	v_subrev_f32_e32 v41, s56, v41
	v_subrev_f32_e32 v42, s56, v42
	v_fmac_f32_e32 v36, v41, v41
	v_fmac_f32_e32 v36, v42, v42
	v_lshlrev_b32_e32 v41, 16, v50
	v_and_b32_e32 v42, 0xffff0000, v50
	v_subrev_f32_e32 v41, s56, v41
	v_subrev_f32_e32 v42, s56, v42
	v_fmac_f32_e32 v36, v41, v41
	v_fmac_f32_e32 v36, v42, v42
	v_lshlrev_b32_e32 v41, 16, v51
	v_and_b32_e32 v42, 0xffff0000, v51
	v_subrev_f32_e32 v41, s56, v41
	v_subrev_f32_e32 v42, s56, v42
	v_fmac_f32_e32 v36, v41, v41
	v_fmac_f32_e32 v36, v42, v42
	v_mov_b32_e32 v37, 0
	v_lshlrev_b32_e32 v41, 16, v52
	v_and_b32_e32 v42, 0xffff0000, v52
	v_subrev_f32_e32 v41, s57, v41
	v_subrev_f32_e32 v42, s57, v42
	v_fmac_f32_e32 v37, v41, v41
	v_fmac_f32_e32 v37, v42, v42
	v_lshlrev_b32_e32 v41, 16, v53
	v_and_b32_e32 v42, 0xffff0000, v53
	v_subrev_f32_e32 v41, s57, v41
	v_subrev_f32_e32 v42, s57, v42
	v_fmac_f32_e32 v37, v41, v41
	v_fmac_f32_e32 v37, v42, v42
	v_lshlrev_b32_e32 v41, 16, v54
	v_and_b32_e32 v42, 0xffff0000, v54
	v_subrev_f32_e32 v41, s57, v41
	v_subrev_f32_e32 v42, s57, v42
	v_fmac_f32_e32 v37, v41, v41
	v_fmac_f32_e32 v37, v42, v42
	v_lshlrev_b32_e32 v41, 16, v55
	v_and_b32_e32 v42, 0xffff0000, v55
	v_subrev_f32_e32 v41, s57, v41
	v_subrev_f32_e32 v42, s57, v42
	v_fmac_f32_e32 v37, v41, v41
	v_fmac_f32_e32 v37, v42, v42
	v_lshlrev_b32_e32 v41, 16, v56
	v_and_b32_e32 v42, 0xffff0000, v56
	v_subrev_f32_e32 v41, s57, v41
	v_subrev_f32_e32 v42, s57, v42
	v_fmac_f32_e32 v37, v41, v41
	v_fmac_f32_e32 v37, v42, v42
	v_lshlrev_b32_e32 v41, 16, v57
	v_and_b32_e32 v42, 0xffff0000, v57
	v_subrev_f32_e32 v41, s57, v41
	v_subrev_f32_e32 v42, s57, v42
	v_fmac_f32_e32 v37, v41, v41
	v_fmac_f32_e32 v37, v42, v42
	v_lshlrev_b32_e32 v41, 16, v58
	v_and_b32_e32 v42, 0xffff0000, v58
	v_subrev_f32_e32 v41, s57, v41
	v_subrev_f32_e32 v42, s57, v42
	v_fmac_f32_e32 v37, v41, v41
	v_fmac_f32_e32 v37, v42, v42
	v_lshlrev_b32_e32 v41, 16, v59
	v_and_b32_e32 v42, 0xffff0000, v59
	v_subrev_f32_e32 v41, s57, v41
	v_subrev_f32_e32 v42, s57, v42
	v_fmac_f32_e32 v37, v41, v41
	v_fmac_f32_e32 v37, v42, v42
	v_mov_b32_e32 v38, 0
	v_lshlrev_b32_e32 v41, 16, v60
	v_and_b32_e32 v42, 0xffff0000, v60
	v_subrev_f32_e32 v41, s58, v41
	v_subrev_f32_e32 v42, s58, v42
	v_fmac_f32_e32 v38, v41, v41
	v_fmac_f32_e32 v38, v42, v42
	v_lshlrev_b32_e32 v41, 16, v61
; __device__ __forceinline__ void mixer_phase(LAS unsigned char* lds, bf16* U  , const bf16* V, const bf16* C, bf16* Bout,
;                                             const bf16* wsb, const float* sgu_b, const float* sgu_g, const bf16* pwT, const float* pool_scale, int G, int bid) {
;     ...
;                 float sq = 0.f;
; #pragma unroll
;                 for (int j = 0; j < 16; ++j) { const float d = x[j] - mean; sq += d * d; }
;                 const float rstd = 1.0f / sqrtf(wave_sum(sq) * (1.f / D) + EPS);
;                 if (lane == 0) { const int sr = wid * 16 + ib + i; stat[2 * sr] = mean; stat[2 * sr + 1] = rstd; }
	v_and_b32_e32 v42, 0xffff0000, v61
	v_subrev_f32_e32 v41, s58, v41
	v_subrev_f32_e32 v42, s58, v42
	v_fmac_f32_e32 v38, v41, v41
	v_fmac_f32_e32 v38, v42, v42
	v_lshlrev_b32_e32 v41, 16, v62
	v_and_b32_e32 v42, 0xffff0000, v62
	v_subrev_f32_e32 v41, s58, v41
	v_subrev_f32_e32 v42, s58, v42
	v_fmac_f32_e32 v38, v41, v41
	v_fmac_f32_e32 v38, v42, v42
	v_lshlrev_b32_e32 v41, 16, v63
	v_and_b32_e32 v42, 0xffff0000, v63
	v_subrev_f32_e32 v41, s58, v41
	v_subrev_f32_e32 v42, s58, v42
	v_fmac_f32_e32 v38, v41, v41
	v_fmac_f32_e32 v38, v42, v42
	v_lshlrev_b32_e32 v41, 16, v64
	v_and_b32_e32 v42, 0xffff0000, v64
	v_subrev_f32_e32 v41, s58, v41
	v_subrev_f32_e32 v42, s58, v42
	v_fmac_f32_e32 v38, v41, v41
	v_fmac_f32_e32 v38, v42, v42
	v_lshlrev_b32_e32 v41, 16, v65
	v_and_b32_e32 v42, 0xffff0000, v65
	v_subrev_f32_e32 v41, s58, v41
	v_subrev_f32_e32 v42, s58, v42
	v_fmac_f32_e32 v38, v41, v41
	v_fmac_f32_e32 v38, v42, v42
	v_lshlrev_b32_e32 v41, 16, v66
	v_and_b32_e32 v42, 0xffff0000, v66
	v_subrev_f32_e32 v41, s58, v41
	v_subrev_f32_e32 v42, s58, v42
	v_fmac_f32_e32 v38, v41, v41
	v_fmac_f32_e32 v38, v42, v42
	v_lshlrev_b32_e32 v41, 16, v67
	v_and_b32_e32 v42, 0xffff0000, v67
	v_subrev_f32_e32 v41, s58, v41
	v_subrev_f32_e32 v42, s58, v42
	v_fmac_f32_e32 v38, v41, v41
	v_fmac_f32_e32 v38, v42, v42
	v_mov_b32_e32 v39, 0
	v_lshlrev_b32_e32 v41, 16, v68
	v_and_b32_e32 v42, 0xffff0000, v68
	v_subrev_f32_e32 v41, s59, v41
	v_subrev_f32_e32 v42, s59, v42
	v_fmac_f32_e32 v39, v41, v41
	v_fmac_f32_e32 v39, v42, v42
	v_lshlrev_b32_e32 v41, 16, v69
	v_and_b32_e32 v42, 0xffff0000, v69
	v_subrev_f32_e32 v41, s59, v41
	v_subrev_f32_e32 v42, s59, v42
	v_fmac_f32_e32 v39, v41, v41
	v_fmac_f32_e32 v39, v42, v42
	v_lshlrev_b32_e32 v41, 16, v70
	v_and_b32_e32 v42, 0xffff0000, v70
	v_subrev_f32_e32 v41, s59, v41
	v_subrev_f32_e32 v42, s59, v42
	v_fmac_f32_e32 v39, v41, v41
	v_fmac_f32_e32 v39, v42, v42
	v_lshlrev_b32_e32 v41, 16, v71
	v_and_b32_e32 v42, 0xffff0000, v71
	v_subrev_f32_e32 v41, s59, v41
	v_subrev_f32_e32 v42, s59, v42
	v_fmac_f32_e32 v39, v41, v41
	v_fmac_f32_e32 v39, v42, v42
	v_lshlrev_b32_e32 v41, 16, v72
	v_and_b32_e32 v42, 0xffff0000, v72
	v_subrev_f32_e32 v41, s59, v41
	v_subrev_f32_e32 v42, s59, v42
	v_fmac_f32_e32 v39, v41, v41
	v_fmac_f32_e32 v39, v42, v42
	v_lshlrev_b32_e32 v41, 16, v73
	v_and_b32_e32 v42, 0xffff0000, v73
	v_subrev_f32_e32 v41, s59, v41
	v_subrev_f32_e32 v42, s59, v42
	v_fmac_f32_e32 v39, v41, v41
	v_fmac_f32_e32 v39, v42, v42
	v_lshlrev_b32_e32 v41, 16, v74
	v_and_b32_e32 v42, 0xffff0000, v74
	v_subrev_f32_e32 v41, s59, v41
	v_subrev_f32_e32 v42, s59, v42
	v_fmac_f32_e32 v39, v41, v41
	v_fmac_f32_e32 v39, v42, v42
	v_lshlrev_b32_e32 v41, 16, v75
	v_and_b32_e32 v42, 0xffff0000, v75
	v_subrev_f32_e32 v41, s59, v41
	v_subrev_f32_e32 v42, s59, v42
	v_fmac_f32_e32 v39, v41, v41
	v_fmac_f32_e32 v39, v42, v42
	s_nop 1
	v_add_f32_dpp v36, v36, v36 quad_perm:[1,0,3,2] row_mask:0xf bank_mask:0xf
	v_add_f32_dpp v37, v37, v37 quad_perm:[1,0,3,2] row_mask:0xf bank_mask:0xf
	v_add_f32_dpp v38, v38, v38 quad_perm:[1,0,3,2] row_mask:0xf bank_mask:0xf
	v_add_f32_dpp v39, v39, v39 quad_perm:[1,0,3,2] row_mask:0xf bank_mask:0xf
	v_add_f32_dpp v36, v36, v36 quad_perm:[2,3,0,1] row_mask:0xf bank_mask:0xf
	v_add_f32_dpp v37, v37, v37 quad_perm:[2,3,0,1] row_mask:0xf bank_mask:0xf
	v_add_f32_dpp v38, v38, v38 quad_perm:[2,3,0,1] row_mask:0xf bank_mask:0xf
	v_add_f32_dpp v39, v39, v39 quad_perm:[2,3,0,1] row_mask:0xf bank_mask:0xf
	v_add_f32_dpp v36, v36, v36 row_half_mirror row_mask:0xf bank_mask:0xf
	v_add_f32_dpp v37, v37, v37 row_half_mirror row_mask:0xf bank_mask:0xf
	v_add_f32_dpp v38, v38, v38 row_half_mirror row_mask:0xf bank_mask:0xf
	v_add_f32_dpp v39, v39, v39 row_half_mirror row_mask:0xf bank_mask:0xf
	v_add_f32_dpp v36, v36, v36 row_mirror row_mask:0xf bank_mask:0xf
	v_add_f32_dpp v37, v37, v37 row_mirror row_mask:0xf bank_mask:0xf
	v_add_f32_dpp v38, v38, v38 row_mirror row_mask:0xf bank_mask:0xf
	v_add_f32_dpp v39, v39, v39 row_mirror row_mask:0xf bank_mask:0xf
	v_add_f32_dpp v36, v36, v36 row_bcast:15 row_mask:0xa bank_mask:0xf
	v_add_f32_dpp v37, v37, v37 row_bcast:15 row_mask:0xa bank_mask:0xf
	v_add_f32_dpp v38, v38, v38 row_bcast:15 row_mask:0xa bank_mask:0xf
	v_add_f32_dpp v39, v39, v39 row_bcast:15 row_mask:0xa bank_mask:0xf
	v_add_f32_dpp v36, v36, v36 row_bcast:31 row_mask:0xc bank_mask:0xf
	v_add_f32_dpp v37, v37, v37 row_bcast:31 row_mask:0xc bank_mask:0xf
	v_add_f32_dpp v38, v38, v38 row_bcast:31 row_mask:0xc bank_mask:0xf
	v_add_f32_dpp v39, v39, v39 row_bcast:31 row_mask:0xc bank_mask:0xf
	v_mul_f32_e32 v36, 0x3a800000, v36
	v_mul_f32_e32 v37, 0x3a800000, v37
	v_mul_f32_e32 v38, 0x3a800000, v38
	v_mul_f32_e32 v39, 0x3a800000, v39
	v_add_f32_e32 v36, 0x358637bd, v36
	v_add_f32_e32 v37, 0x358637bd, v37
	v_add_f32_e32 v38, 0x358637bd, v38
	v_add_f32_e32 v39, 0x358637bd, v39
	v_rsq_f32_e32 v36, v36
	v_rsq_f32_e32 v37, v37
	v_rsq_f32_e32 v38, v38
	v_rsq_f32_e32 v39, v39
	s_nop 0
	v_readlane_b32 s62, v36, 63
	v_readlane_b32 s63, v37, 63
	v_readlane_b32 s64, v38, 63
	v_readlane_b32 s65, v39, 63
	s_nop 3
	v_writelane_b32 v78, s56, 0
	v_writelane_b32 v79, s62, 0
	v_writelane_b32 v78, s57, 1
	v_writelane_b32 v79, s63, 1
	v_writelane_b32 v78, s58, 2
	v_writelane_b32 v79, s64, 2
	v_writelane_b32 v78, s59, 3
	v_writelane_b32 v79, s65, 3
	s_mov_b64 exec, 15
	ds_write_b64 v80, v[78:79] offset:96
	s_mov_b64 exec, -1
